# out-GEMM / MLP-down epilogue tiles (X, XN, split-K slabs) stored write-through (sc0 sc1) so the grid barrier's L2 write-back finds little dirty data
# speedup vs baseline: 1.0010x; 1.0010x over previous
; __device__ __forceinline__ unsigned cvt_pk_bf16(float lo, float hi) { unsigned r; asm volatile("v_cvt_pk_bf16_f32 %0, %1, %2" : "=v"(r) : "v"(lo), "v"(hi)); return r; }
;     __device__ __forceinline__ void operator()(f32x4 (&acc)[2][2][4][2], const Unit& u, int wr, int wc, int fr, int fq) const {
;         if (u.sw) {
;             bf16_t* base = (bf16_t*)slab + (size_t)(((u.pm - 32) * 8 + u.pn) * 8 + u.ks) * 65536 + (size_t)(wr * 64 + fr) * 256 + wc * 32 + 8 * fq;
; #pragma unroll
;             for (int ai = 0; ai < 2; ++ai)
; #pragma unroll
;                 for (int m = 0; m < 4; ++m)
; #pragma unroll
;                     for (int bj = 0; bj < 2; ++bj) { const f32x4 v0 = acc[ai][bj][m][0], v1 = acc[ai][bj][m][1];
;                         u32x4 w; w.x = cvt_pk_bf16(v0[0], v0[1]); w.y = cvt_pk_bf16(v0[2], v0[3]); w.z = cvt_pk_bf16(v1[0], v1[1]); w.w = cvt_pk_bf16(v1[2], v1[3]);
;                         *(u32x4*)(base + (size_t)(ai * HALF + m * 16) * 256 + bj * HALF) = w; }
;             return;
.LBB9_1153:
	v_mov_b32_e32 v249, v0
	s_nop 0
	v_readfirstlane_b32 s4, v249
	s_ashr_i32 s40, s4, 8
	s_bfe_u32 s41, s4, 0x20006
	v_and_b32_e32 v248, 15, v249
	s_cmp_eq_u32 s45, 0
	v_bfe_u32 v250, v249, 4, 2
	s_cbranch_scc1 .LBB9_1193
	s_lshl_b32 s9, s44, 3
	s_lshl_b32 s3, s91, 6
	s_add_i32 s5, s5, s9
	s_add_i32 s3, s5, s3
	s_add_i32 s34, s3, 0xfffff800
	s_ashr_i32 s35, s34, 31
	s_lshl_b64 s[34:35], s[34:35], 17
	v_lshl_or_b32 v130, s40, 6, v248
	s_add_u32 s34, s77, s34
	v_ashrrev_i32_e32 v131, 31, v130
	s_addc_u32 s35, s78, s35
	v_lshlrev_b64 v[130:131], 9, v[130:131]
	v_lshl_add_u64 v[130:131], s[34:35], 0, v[130:131]
	s_lshl_b32 s48, s41, 6
	v_lshl_add_u64 v[130:131], v[130:131], 0, s[48:49]
	v_lshlrev_b32_e32 v186, 4, v250
	v_lshl_add_u64 v[130:131], v[130:131], 0, v[186:187]
	v_cvt_pk_bf16_f32 v132, v126, v127
	v_cvt_pk_bf16_f32 v133, v128, v129
	v_cvt_pk_bf16_f32 v134, v122, v123
	v_cvt_pk_bf16_f32 v135, v124, v125
	global_store_dwordx4 v[130:131], v[132:135], off sc0 sc1
	v_add_co_u32_e32 v136, vcc, s28, v130
	s_nop 0
	v_cvt_pk_bf16_f32 v132, v118, v119
	v_cvt_pk_bf16_f32 v133, v120, v121
	v_cvt_pk_bf16_f32 v134, v114, v115
	v_cvt_pk_bf16_f32 v135, v116, v117
	global_store_dwordx4 v[130:131], v[132:135], off offset:256 sc0 sc1
	v_addc_co_u32_e32 v137, vcc, 0, v131, vcc
	s_nop 0
	v_cvt_pk_bf16_f32 v132, v110, v111
	v_cvt_pk_bf16_f32 v133, v112, v113
	v_cvt_pk_bf16_f32 v134, v106, v107
	v_cvt_pk_bf16_f32 v135, v108, v109
	s_movk_i32 s3, 0x4000
	global_store_dwordx4 v[136:137], v[132:135], off sc0 sc1
	s_nop 1
	v_cvt_pk_bf16_f32 v132, v102, v103
	v_cvt_pk_bf16_f32 v133, v104, v105
	v_cvt_pk_bf16_f32 v134, v98, v99
	v_cvt_pk_bf16_f32 v135, v100, v101
	global_store_dwordx4 v[136:137], v[132:135], off offset:256 sc0 sc1
	v_add_co_u32_e32 v136, vcc, s3, v130
	s_nop 0
	v_cvt_pk_bf16_f32 v132, v94, v95
	v_cvt_pk_bf16_f32 v133, v96, v97
	v_cvt_pk_bf16_f32 v134, v90, v91
	v_cvt_pk_bf16_f32 v135, v92, v93
	s_nop 0
	v_addc_co_u32_e32 v137, vcc, 0, v131, vcc
	s_movk_i32 s3, 0x6000
	global_store_dwordx4 v[136:137], v[132:135], off sc0 sc1
	s_nop 1
	v_cvt_pk_bf16_f32 v132, v86, v87
	v_cvt_pk_bf16_f32 v133, v88, v89
	v_cvt_pk_bf16_f32 v134, v82, v83
	v_cvt_pk_bf16_f32 v135, v84, v85
	global_store_dwordx4 v[136:137], v[132:135], off offset:256 sc0 sc1
	v_add_co_u32_e32 v136, vcc, s3, v130
	s_nop 0
	v_cvt_pk_bf16_f32 v132, v78, v79
	v_cvt_pk_bf16_f32 v133, v80, v81
	v_cvt_pk_bf16_f32 v134, v74, v75
	v_cvt_pk_bf16_f32 v135, v76, v77
	s_nop 0
	v_addc_co_u32_e32 v137, vcc, 0, v131, vcc
	global_store_dwordx4 v[136:137], v[132:135], off sc0 sc1
	s_mov_b32 s3, 0x12000
	s_nop 0
	v_cvt_pk_bf16_f32 v132, v70, v71
	v_cvt_pk_bf16_f32 v133, v72, v73
	v_cvt_pk_bf16_f32 v134, v66, v67
	v_cvt_pk_bf16_f32 v135, v68, v69
	global_store_dwordx4 v[136:137], v[132:135], off offset:256 sc0 sc1
	v_add_co_u32_e32 v136, vcc, s59, v130
	s_nop 0
	v_cvt_pk_bf16_f32 v132, v62, v63
	v_cvt_pk_bf16_f32 v133, v64, v65
	v_cvt_pk_bf16_f32 v134, v58, v59
	v_cvt_pk_bf16_f32 v135, v60, v61
	s_nop 0
	v_addc_co_u32_e32 v137, vcc, 0, v131, vcc
	global_store_dwordx4 v[136:137], v[132:135], off sc0 sc1
	s_nop 1
	v_cvt_pk_bf16_f32 v132, v54, v55
	v_cvt_pk_bf16_f32 v133, v56, v57
	v_cvt_pk_bf16_f32 v134, v50, v51
	v_cvt_pk_bf16_f32 v135, v52, v53
	global_store_dwordx4 v[136:137], v[132:135], off offset:256 sc0 sc1
	v_add_co_u32_e32 v136, vcc, s3, v130
	s_nop 0
	v_cvt_pk_bf16_f32 v132, v46, v47
	v_cvt_pk_bf16_f32 v133, v48, v49
	v_cvt_pk_bf16_f32 v134, v42, v43
	v_cvt_pk_bf16_f32 v135, v44, v45
	s_nop 0
	v_addc_co_u32_e32 v137, vcc, 0, v131, vcc
	s_mov_b32 s3, 0x14000
	global_store_dwordx4 v[136:137], v[132:135], off sc0 sc1
	s_nop 1
	v_cvt_pk_bf16_f32 v132, v38, v39
	v_cvt_pk_bf16_f32 v133, v40, v41
	v_cvt_pk_bf16_f32 v134, v34, v35
	v_cvt_pk_bf16_f32 v135, v36, v37
	global_store_dwordx4 v[136:137], v[132:135], off offset:256 sc0 sc1
	v_add_co_u32_e32 v136, vcc, s3, v130
	s_nop 0
	v_cvt_pk_bf16_f32 v132, v30, v31
	v_cvt_pk_bf16_f32 v133, v32, v33
	v_cvt_pk_bf16_f32 v134, v26, v27
	v_cvt_pk_bf16_f32 v135, v28, v29
	s_nop 0
	v_addc_co_u32_e32 v137, vcc, 0, v131, vcc
	s_mov_b32 s3, 0x16000
	global_store_dwordx4 v[136:137], v[132:135], off sc0 sc1
	s_nop 1
	v_cvt_pk_bf16_f32 v132, v22, v23
	v_cvt_pk_bf16_f32 v133, v24, v25
	v_cvt_pk_bf16_f32 v134, v18, v19
	v_cvt_pk_bf16_f32 v135, v20, v21
	global_store_dwordx4 v[136:137], v[132:135], off offset:256 sc0 sc1
	v_add_co_u32_e32 v136, vcc, s3, v130
	s_nop 0
	v_cvt_pk_bf16_f32 v132, v14, v15
	v_cvt_pk_bf16_f32 v133, v16, v17
	v_cvt_pk_bf16_f32 v134, v10, v11
	v_cvt_pk_bf16_f32 v135, v12, v13
	s_nop 0
	v_addc_co_u32_e32 v137, vcc, 0, v131, vcc
	global_store_dwordx4 v[136:137], v[132:135], off sc0 sc1
	v_cvt_pk_bf16_f32 v130, v6, v7
	v_cvt_pk_bf16_f32 v131, v8, v9
	s_nop 1
	v_cvt_pk_bf16_f32 v132, v2, v3
	v_cvt_pk_bf16_f32 v133, v4, v5
	global_store_dwordx4 v[136:137], v[130:133], off offset:256 sc0 sc1
	s_cbranch_execnz .LBB9_1194

; __device__ __forceinline__ unsigned cvt_pk_bf16(float lo, float hi) { unsigned r; asm volatile("v_cvt_pk_bf16_f32 %0, %1, %2" : "=v"(r) : "v"(lo), "v"(hi)); return r; }
;     __device__ __forceinline__ void fuse_tail(f32x4 (&acc)[2][2][4][2], const float (&ssq)[2][4], const Unit& u, int wr, int wc, int fr, int fq, int mi, int row0, int col0) const {
;     ...
;         if (FUSE == 1 && !XF32) {
;             int r0o = row0; asm volatile("" : "+v"(r0o)); bf16_t* xb = X + (size_t)r0o * D + col0;
; #pragma unroll
;             for (int ai = 0; ai < 2; ++ai)
; #pragma unroll
;                 for (int m = 0; m < 4; ++m)
; #pragma unroll
;                     for (int bj = 0; bj < 2; ++bj) { const f32x4 v0 = acc[ai][bj][m][0], v1 = acc[ai][bj][m][1];
;                         u32x4 w; w.x = cvt_pk_bf16(v0[0], v0[1]); w.y = cvt_pk_bf16(v0[2], v0[3]); w.z = cvt_pk_bf16(v1[0], v1[1]); w.w = cvt_pk_bf16(v1[2], v1[3]);
;                         *(u32x4*)(xb + (size_t)(ai * HALF + m * 16) * D + bj * HALF) = w; }
;         }
.LBB9_1176:
	s_or_b64 exec, exec, s[34:35]
	v_cvt_pk_bf16_f32 v114, v232, v233
	v_cvt_pk_bf16_f32 v115, v230, v231
	v_cvt_pk_bf16_f32 v116, v228, v229
	v_cvt_pk_bf16_f32 v117, v226, v227
	s_mov_b32 s3, 0x30000
	v_ashrrev_i32_e32 v237, 31, v236
	v_lshlrev_b64 v[4:5], 12, v[236:237]
	v_lshl_add_u64 v[4:5], s[42:43], 0, v[4:5]
	v_lshl_add_u64 v[4:5], v[234:235], 1, v[4:5]
	global_store_dwordx4 v[4:5], v[114:117], off sc0 sc1
	v_add_co_u32_e32 v8, vcc, s59, v4
	s_nop 0
	v_cvt_pk_bf16_f32 v114, v208, v209
	v_cvt_pk_bf16_f32 v115, v206, v207
	v_cvt_pk_bf16_f32 v116, v204, v205
	v_cvt_pk_bf16_f32 v117, v202, v203
	global_store_dwordx4 v[4:5], v[114:117], off offset:256 sc0 sc1
	v_addc_co_u32_e32 v9, vcc, 0, v5, vcc
	s_nop 0
	v_cvt_pk_bf16_f32 v114, v110, v111
	v_cvt_pk_bf16_f32 v115, v112, v113
	v_cvt_pk_bf16_f32 v116, v106, v107
	v_cvt_pk_bf16_f32 v117, v108, v109
	global_store_dwordx4 v[8:9], v[114:117], off sc0 sc1
	s_cmp_lg_u32 s54, 0
	s_nop 0
	v_cvt_pk_bf16_f32 v114, v102, v103
	v_cvt_pk_bf16_f32 v115, v104, v105
	v_cvt_pk_bf16_f32 v116, v98, v99
	v_cvt_pk_bf16_f32 v117, v100, v101
	global_store_dwordx4 v[8:9], v[114:117], off offset:256 sc0 sc1
	v_add_co_u32_e32 v8, vcc, s56, v4
	s_nop 0
	v_cvt_pk_bf16_f32 v114, v94, v95
	v_cvt_pk_bf16_f32 v115, v96, v97
	v_cvt_pk_bf16_f32 v116, v90, v91
	v_cvt_pk_bf16_f32 v117, v92, v93
	s_nop 0
	v_addc_co_u32_e32 v9, vcc, 0, v5, vcc
	global_store_dwordx4 v[8:9], v[114:117], off sc0 sc1
	s_nop 1
	v_cvt_pk_bf16_f32 v114, v86, v87
	v_cvt_pk_bf16_f32 v115, v88, v89
	v_cvt_pk_bf16_f32 v116, v82, v83
	v_cvt_pk_bf16_f32 v117, v84, v85
	global_store_dwordx4 v[8:9], v[114:117], off offset:256 sc0 sc1
	v_add_co_u32_e32 v8, vcc, s3, v4
	s_nop 0
	v_cvt_pk_bf16_f32 v114, v78, v79
	v_cvt_pk_bf16_f32 v115, v80, v81
	v_cvt_pk_bf16_f32 v116, v74, v75
	v_cvt_pk_bf16_f32 v117, v76, v77
	s_nop 0
	v_addc_co_u32_e32 v9, vcc, 0, v5, vcc
	global_store_dwordx4 v[8:9], v[114:117], off sc0 sc1
	s_mov_b32 s3, 0x90000
	s_nop 0
	v_cvt_pk_bf16_f32 v114, v70, v71
	v_cvt_pk_bf16_f32 v115, v72, v73
	v_cvt_pk_bf16_f32 v116, v66, v67
	v_cvt_pk_bf16_f32 v117, v68, v69
	global_store_dwordx4 v[8:9], v[114:117], off offset:256 sc0 sc1
	v_add_co_u32_e32 v8, vcc, s7, v4
	s_nop 0
	v_cvt_pk_bf16_f32 v114, v62, v63
	v_cvt_pk_bf16_f32 v115, v64, v65
	v_cvt_pk_bf16_f32 v116, v58, v59
	v_cvt_pk_bf16_f32 v117, v60, v61
	s_nop 0
	v_addc_co_u32_e32 v9, vcc, 0, v5, vcc
	global_store_dwordx4 v[8:9], v[114:117], off sc0 sc1
	s_nop 1
	v_cvt_pk_bf16_f32 v114, v54, v55
	v_cvt_pk_bf16_f32 v115, v56, v57
	v_cvt_pk_bf16_f32 v116, v50, v51
	v_cvt_pk_bf16_f32 v117, v52, v53
	global_store_dwordx4 v[8:9], v[114:117], off offset:256 sc0 sc1
	v_add_co_u32_e32 v8, vcc, s3, v4
	s_nop 0
	v_cvt_pk_bf16_f32 v114, v46, v47
	v_cvt_pk_bf16_f32 v115, v48, v49
	v_cvt_pk_bf16_f32 v116, v42, v43
	v_cvt_pk_bf16_f32 v117, v44, v45
	s_nop 0
	v_addc_co_u32_e32 v9, vcc, 0, v5, vcc
	global_store_dwordx4 v[8:9], v[114:117], off sc0 sc1
	s_mov_b32 s3, 0xb0000
	s_nop 0
	v_cvt_pk_bf16_f32 v114, v38, v39
	v_cvt_pk_bf16_f32 v115, v40, v41
	v_cvt_pk_bf16_f32 v116, v34, v35
	v_cvt_pk_bf16_f32 v117, v36, v37
	global_store_dwordx4 v[8:9], v[114:117], off offset:256 sc0 sc1
	v_add_co_u32_e32 v8, vcc, s95, v4
	s_nop 0
	v_cvt_pk_bf16_f32 v114, v30, v31
	v_cvt_pk_bf16_f32 v115, v32, v33
	v_cvt_pk_bf16_f32 v116, v26, v27
	v_cvt_pk_bf16_f32 v117, v28, v29
	s_nop 0
	v_addc_co_u32_e32 v9, vcc, 0, v5, vcc
	global_store_dwordx4 v[8:9], v[114:117], off sc0 sc1
	v_add_co_u32_e32 v4, vcc, s3, v4
	s_nop 0
	v_cvt_pk_bf16_f32 v114, v22, v23
	v_cvt_pk_bf16_f32 v115, v24, v25
	v_cvt_pk_bf16_f32 v116, v18, v19
	v_cvt_pk_bf16_f32 v117, v20, v21
	global_store_dwordx4 v[8:9], v[114:117], off offset:256 sc0 sc1
	v_addc_co_u32_e32 v5, vcc, 0, v5, vcc
	s_nop 0
	v_cvt_pk_bf16_f32 v114, v122, v123
	v_cvt_pk_bf16_f32 v115, v118, v119
	v_cvt_pk_bf16_f32 v116, v124, v125
	v_cvt_pk_bf16_f32 v117, v120, v121
	global_store_dwordx4 v[4:5], v[114:117], off sc0 sc1
	s_nop 1
	v_cvt_pk_bf16_f32 v114, v16, v17
	v_cvt_pk_bf16_f32 v115, v12, v13
	v_cvt_pk_bf16_f32 v116, v14, v15
	v_cvt_pk_bf16_f32 v117, v10, v11
	global_store_dwordx4 v[4:5], v[114:117], off offset:256 sc0 sc1
	s_cbranch_scc1 .LBB9_1196
	s_mov_b32 s34, 0x40001
	s_branch .LBB9_1179

; __device__ __forceinline__ unsigned cvt_pk_bf16(float lo, float hi) { unsigned r; asm volatile("v_cvt_pk_bf16_f32 %0, %1, %2" : "=v"(r) : "v"(lo), "v"(hi)); return r; }
;     __device__ __forceinline__ void fuse_tail(f32x4 (&acc)[2][2][4][2], const float (&ssq)[2][4], const Unit& u, int wr, int wc, int fr, int fq, int mi, int row0, int col0) const {
;     ...
;         bf16_t* XN = (bf16_t*)((char*)X + RN_DXN);
;         const float* sh = mods_l + nsh_off + (size_t)mi * MODW + col0;
; #pragma unroll
;         for (int bj = 0; bj < 2; ++bj) { f32x4 GG[2], SS[2];
; #pragma unroll
;             for (int n = 0; n < 2; ++n) { GG[n] = *(const f32x4*)(ng + col0 + bj * HALF + 4 * n) * (*(const f32x4*)(sh + D + bj * HALF + 4 * n) + 1.f); SS[n] = *(const f32x4*)(sh + bj * HALF + 4 * n); }
; #pragma unroll
;             for (int ai = 0; ai < 2; ++ai)
; #pragma unroll
;                 for (int m = 0; m < 4; ++m) { const float rstd = S[ai * HALF + wr * 64 + m * 16 + fr];
;                     const f32x4 h0 = acc[ai][bj][m][0] * rstd * GG[0] + SS[0], h1 = acc[ai][bj][m][1] * rstd * GG[1] + SS[1];
;                     u32x4 w; w.x = cvt_pk_bf16(h0[0], h0[1]); w.y = cvt_pk_bf16(h0[2], h0[3]); w.z = cvt_pk_bf16(h1[0], h1[1]); w.w = cvt_pk_bf16(h1[2], h1[3]);
;                     *(u32x4*)(XN + (size_t)(row0 + ai * HALF + m * 16) * D + col0 + bj * HALF) = w; } }
.LBB9_1198:
	s_or_b64 exec, exec, s[44:45]
	s_add_u32 s34, s85, s48
	s_addc_u32 s35, s86, s5
	v_lshlrev_b64 v[2:3], 2, v[234:235]
	v_lshl_add_u64 v[114:115], s[34:35], 0, v[2:3]
	s_and_b32 s3, s4, 0xffffff00
	s_add_i32 s3, s3, 0
	v_add_co_u32_e32 v128, vcc, s28, v114
	s_waitcnt lgkmcnt(0)
	s_barrier
	s_mov_b64 s[34:35], 0x2000
	v_lshl_add_u32 v4, v248, 2, s3
	v_lshl_add_u64 v[116:117], s[20:21], 0, v[2:3]
	v_addc_co_u32_e32 v129, vcc, 0, v115, vcc
	v_lshl_add_u64 v[130:131], v[114:115], 0, s[34:35]
	v_add_u32_e32 v140, 0x22000, v4
	global_load_dwordx4 v[142:145], v[116:117], off offset:16
	global_load_dwordx4 v[2:5], v[116:117], off
	global_load_dwordx4 v[6:9], v[128:129], off
	global_load_dwordx4 v[136:139], v[130:131], off offset:16
	v_lshl_add_u64 v[126:127], v[234:235], 1, s[26:27]
	s_mov_b64 s[4:5], 0x2200
	s_waitcnt vmcnt(1)
	v_pk_add_f32 v[8:9], v[8:9], 1.0 op_sel_hi:[1,0]
	v_pk_add_f32 v[6:7], v[6:7], 1.0 op_sel_hi:[1,0]
	v_pk_mul_f32 v[132:133], v[4:5], v[8:9]
	v_pk_mul_f32 v[134:135], v[2:3], v[6:7]
	global_load_dwordx4 v[2:5], v[114:115], off offset:16
	global_load_dwordx4 v[6:9], v[114:115], off
	s_waitcnt vmcnt(2)
	v_pk_add_f32 v[130:131], v[138:139], 1.0 op_sel_hi:[1,0]
	v_pk_add_f32 v[138:139], v[136:137], 1.0 op_sel_hi:[1,0]
	v_pk_mul_f32 v[136:137], v[144:145], v[130:131]
	ds_read_b32 v130, v140
	v_pk_mul_f32 v[138:139], v[142:143], v[138:139]
	s_waitcnt lgkmcnt(0)
	v_pk_mul_f32 v[142:143], v[230:231], v[130:131] op_sel_hi:[1,0]
	v_pk_mul_f32 v[144:145], v[232:233], v[130:131] op_sel_hi:[1,0]
	s_waitcnt vmcnt(0)
	v_pk_fma_f32 v[146:147], v[132:133], v[142:143], v[8:9]
	v_pk_fma_f32 v[142:143], v[134:135], v[144:145], v[6:7]
	v_pk_mul_f32 v[144:145], v[226:227], v[130:131] op_sel_hi:[1,0]
	v_pk_mul_f32 v[130:131], v[228:229], v[130:131] op_sel_hi:[1,0]
	v_pk_fma_f32 v[148:149], v[136:137], v[144:145], v[4:5]
	v_pk_fma_f32 v[130:131], v[138:139], v[130:131], v[2:3]
	v_cvt_pk_bf16_f32 v142, v142, v143
	v_cvt_pk_bf16_f32 v143, v146, v147
	s_nop 0
	v_cvt_pk_bf16_f32 v144, v130, v131
	v_lshl_add_u64 v[130:131], v[126:127], 0, v[224:225]
	v_cvt_pk_bf16_f32 v145, v148, v149
	global_store_dwordx4 v[130:131], v[142:145], off sc0 sc1
	ds_read_b32 v142, v140 offset:64
	s_waitcnt lgkmcnt(0)
	v_pk_mul_f32 v[110:111], v[110:111], v[142:143] op_sel_hi:[1,0]
	v_pk_mul_f32 v[106:107], v[106:107], v[142:143] op_sel_hi:[1,0]
	v_pk_mul_f32 v[112:113], v[112:113], v[142:143] op_sel_hi:[1,0]
	v_pk_fma_f32 v[110:111], v[134:135], v[110:111], v[6:7]
	v_pk_mul_f32 v[108:109], v[108:109], v[142:143] op_sel_hi:[1,0]
	v_pk_fma_f32 v[106:107], v[138:139], v[106:107], v[2:3]
	v_pk_fma_f32 v[112:113], v[132:133], v[112:113], v[8:9]
	v_pk_fma_f32 v[142:143], v[136:137], v[108:109], v[4:5]
	v_cvt_pk_bf16_f32 v108, v110, v111
	v_cvt_pk_bf16_f32 v109, v112, v113
	v_cvt_pk_bf16_f32 v110, v106, v107
	v_lshl_add_u64 v[106:107], v[126:127], 0, v[222:223]
	v_cvt_pk_bf16_f32 v111, v142, v143
	global_store_dwordx4 v[106:107], v[108:111], off sc0 sc1
	ds_read_b32 v108, v140 offset:128
	s_waitcnt lgkmcnt(0)
	v_pk_mul_f32 v[94:95], v[94:95], v[108:109] op_sel_hi:[1,0]
	v_pk_mul_f32 v[90:91], v[90:91], v[108:109] op_sel_hi:[1,0]
	v_pk_mul_f32 v[96:97], v[96:97], v[108:109] op_sel_hi:[1,0]
	v_pk_fma_f32 v[94:95], v[134:135], v[94:95], v[6:7]
	v_pk_mul_f32 v[92:93], v[92:93], v[108:109] op_sel_hi:[1,0]
	v_pk_fma_f32 v[90:91], v[138:139], v[90:91], v[2:3]
	v_pk_fma_f32 v[96:97], v[132:133], v[96:97], v[8:9]
	v_pk_fma_f32 v[108:109], v[136:137], v[92:93], v[4:5]
	v_cvt_pk_bf16_f32 v92, v94, v95
	v_cvt_pk_bf16_f32 v93, v96, v97
	v_cvt_pk_bf16_f32 v94, v90, v91
	v_lshl_add_u64 v[90:91], v[126:127], 0, v[220:221]
	v_cvt_pk_bf16_f32 v95, v108, v109
	global_store_dwordx4 v[90:91], v[92:95], off sc0 sc1
	ds_read_b32 v92, v140 offset:192
	s_waitcnt lgkmcnt(0)
	v_pk_mul_f32 v[78:79], v[78:79], v[92:93] op_sel_hi:[1,0]
	v_pk_mul_f32 v[74:75], v[74:75], v[92:93] op_sel_hi:[1,0]
	v_pk_mul_f32 v[80:81], v[80:81], v[92:93] op_sel_hi:[1,0]
	v_pk_fma_f32 v[78:79], v[134:135], v[78:79], v[6:7]
	v_pk_mul_f32 v[76:77], v[76:77], v[92:93] op_sel_hi:[1,0]
	v_pk_fma_f32 v[74:75], v[138:139], v[74:75], v[2:3]
	v_pk_fma_f32 v[80:81], v[132:133], v[80:81], v[8:9]
	v_pk_fma_f32 v[92:93], v[136:137], v[76:77], v[4:5]
	v_cvt_pk_bf16_f32 v76, v78, v79
	v_cvt_pk_bf16_f32 v77, v80, v81
	v_cvt_pk_bf16_f32 v78, v74, v75
	v_lshl_add_u64 v[74:75], v[126:127], 0, v[216:217]
	v_cvt_pk_bf16_f32 v79, v92, v93
	global_store_dwordx4 v[74:75], v[76:79], off sc0 sc1
	ds_read_b32 v76, v140 offset:512
	s_waitcnt lgkmcnt(0)
	v_pk_mul_f32 v[62:63], v[62:63], v[76:77] op_sel_hi:[1,0]
	v_pk_mul_f32 v[58:59], v[58:59], v[76:77] op_sel_hi:[1,0]
	v_pk_mul_f32 v[64:65], v[64:65], v[76:77] op_sel_hi:[1,0]
	v_pk_fma_f32 v[62:63], v[134:135], v[62:63], v[6:7]
	v_pk_mul_f32 v[60:61], v[60:61], v[76:77] op_sel_hi:[1,0]
	v_pk_fma_f32 v[58:59], v[138:139], v[58:59], v[2:3]
	v_pk_fma_f32 v[64:65], v[132:133], v[64:65], v[8:9]
	v_pk_fma_f32 v[76:77], v[136:137], v[60:61], v[4:5]
	v_cvt_pk_bf16_f32 v60, v62, v63
	v_cvt_pk_bf16_f32 v61, v64, v65
	v_cvt_pk_bf16_f32 v62, v58, v59
	v_lshl_add_u64 v[58:59], v[126:127], 0, v[218:219]
	v_cvt_pk_bf16_f32 v63, v76, v77
	global_store_dwordx4 v[58:59], v[60:63], off sc0 sc1
	ds_read_b32 v60, v140 offset:576
	s_waitcnt lgkmcnt(0)
; __device__ __forceinline__ unsigned cvt_pk_bf16(float lo, float hi) { unsigned r; asm volatile("v_cvt_pk_bf16_f32 %0, %1, %2" : "=v"(r) : "v"(lo), "v"(hi)); return r; }
;     __device__ __forceinline__ void fuse_tail(f32x4 (&acc)[2][2][4][2], const float (&ssq)[2][4], const Unit& u, int wr, int wc, int fr, int fq, int mi, int row0, int col0) const {
;     ...
;         bf16_t* XN = (bf16_t*)((char*)X + RN_DXN);
;         const float* sh = mods_l + nsh_off + (size_t)mi * MODW + col0;
; #pragma unroll
;         for (int bj = 0; bj < 2; ++bj) { f32x4 GG[2], SS[2];
; #pragma unroll
;             for (int n = 0; n < 2; ++n) { GG[n] = *(const f32x4*)(ng + col0 + bj * HALF + 4 * n) * (*(const f32x4*)(sh + D + bj * HALF + 4 * n) + 1.f); SS[n] = *(const f32x4*)(sh + bj * HALF + 4 * n); }
; #pragma unroll
;             for (int ai = 0; ai < 2; ++ai)
; #pragma unroll
;                 for (int m = 0; m < 4; ++m) { const float rstd = S[ai * HALF + wr * 64 + m * 16 + fr];
;                     const f32x4 h0 = acc[ai][bj][m][0] * rstd * GG[0] + SS[0], h1 = acc[ai][bj][m][1] * rstd * GG[1] + SS[1];
;                     u32x4 w; w.x = cvt_pk_bf16(h0[0], h0[1]); w.y = cvt_pk_bf16(h0[2], h0[3]); w.z = cvt_pk_bf16(h1[0], h1[1]); w.w = cvt_pk_bf16(h1[2], h1[3]);
;                     *(u32x4*)(XN + (size_t)(row0 + ai * HALF + m * 16) * D + col0 + bj * HALF) = w; } }
	v_pk_mul_f32 v[46:47], v[46:47], v[60:61] op_sel_hi:[1,0]
	v_pk_mul_f32 v[42:43], v[42:43], v[60:61] op_sel_hi:[1,0]
	v_pk_mul_f32 v[48:49], v[48:49], v[60:61] op_sel_hi:[1,0]
	v_pk_fma_f32 v[46:47], v[134:135], v[46:47], v[6:7]
	v_pk_mul_f32 v[44:45], v[44:45], v[60:61] op_sel_hi:[1,0]
	v_pk_fma_f32 v[42:43], v[138:139], v[42:43], v[2:3]
	v_pk_fma_f32 v[48:49], v[132:133], v[48:49], v[8:9]
	v_pk_fma_f32 v[60:61], v[136:137], v[44:45], v[4:5]
	v_cvt_pk_bf16_f32 v44, v46, v47
	v_cvt_pk_bf16_f32 v45, v48, v49
	v_cvt_pk_bf16_f32 v46, v42, v43
	v_lshl_add_u64 v[42:43], v[126:127], 0, v[214:215]
	v_cvt_pk_bf16_f32 v47, v60, v61
	global_store_dwordx4 v[42:43], v[44:47], off sc0 sc1
	ds_read_b32 v44, v140 offset:640
	s_waitcnt lgkmcnt(0)
	v_pk_mul_f32 v[30:31], v[30:31], v[44:45] op_sel_hi:[1,0]
	v_pk_mul_f32 v[26:27], v[26:27], v[44:45] op_sel_hi:[1,0]
	v_pk_mul_f32 v[32:33], v[32:33], v[44:45] op_sel_hi:[1,0]
	v_pk_fma_f32 v[30:31], v[134:135], v[30:31], v[6:7]
	v_pk_mul_f32 v[28:29], v[28:29], v[44:45] op_sel_hi:[1,0]
	v_pk_fma_f32 v[26:27], v[138:139], v[26:27], v[2:3]
	v_pk_fma_f32 v[32:33], v[132:133], v[32:33], v[8:9]
	v_pk_fma_f32 v[44:45], v[136:137], v[28:29], v[4:5]
	v_cvt_pk_bf16_f32 v28, v30, v31
	v_cvt_pk_bf16_f32 v29, v32, v33
	v_cvt_pk_bf16_f32 v30, v26, v27
	v_lshl_add_u64 v[26:27], v[126:127], 0, v[212:213]
	v_cvt_pk_bf16_f32 v31, v44, v45
	global_store_dwordx4 v[26:27], v[28:31], off sc0 sc1
	ds_read_b32 v28, v140 offset:704
	s_waitcnt lgkmcnt(0)
	v_pk_mul_f32 v[32:33], v[122:123], v[28:29] op_sel_hi:[1,0]
	v_pk_mul_f32 v[30:31], v[118:119], v[28:29] op_sel_hi:[1,0]
	v_pk_fma_f32 v[6:7], v[134:135], v[32:33], v[6:7]
	v_pk_fma_f32 v[8:9], v[132:133], v[30:31], v[8:9]
	v_pk_mul_f32 v[30:31], v[120:121], v[28:29] op_sel_hi:[1,0]
	v_pk_mul_f32 v[28:29], v[124:125], v[28:29] op_sel_hi:[1,0]
	v_pk_fma_f32 v[30:31], v[136:137], v[30:31], v[4:5]
	v_pk_fma_f32 v[4:5], v[138:139], v[28:29], v[2:3]
	v_lshl_add_u64 v[28:29], v[126:127], 0, v[210:211]
	v_cvt_pk_bf16_f32 v2, v6, v7
	v_cvt_pk_bf16_f32 v3, v8, v9
	v_cvt_pk_bf16_f32 v4, v4, v5
	v_cvt_pk_bf16_f32 v5, v30, v31
	global_store_dwordx4 v[28:29], v[2:5], off sc0 sc1
	v_lshl_add_u64 v[30:31], v[114:115], 0, s[4:5]
	global_load_dwordx4 v[46:49], v[116:117], off offset:528
	global_load_dwordx4 v[2:5], v[116:117], off offset:512
	global_load_dwordx4 v[6:9], v[128:129], off offset:512
	global_load_dwordx4 v[60:63], v[30:31], off offset:16
	s_waitcnt vmcnt(1)
	v_pk_add_f32 v[8:9], v[8:9], 1.0 op_sel_hi:[1,0]
	v_pk_add_f32 v[6:7], v[6:7], 1.0 op_sel_hi:[1,0]
	v_pk_mul_f32 v[30:31], v[4:5], v[8:9]
	v_pk_mul_f32 v[32:33], v[2:3], v[6:7]
	global_load_dwordx4 v[2:5], v[114:115], off offset:528
	global_load_dwordx4 v[6:9], v[114:115], off offset:512
	s_waitcnt vmcnt(2)
	v_pk_add_f32 v[44:45], v[62:63], 1.0 op_sel_hi:[1,0]
	v_pk_add_f32 v[60:61], v[60:61], 1.0 op_sel_hi:[1,0]
	v_pk_mul_f32 v[44:45], v[48:49], v[44:45]
	ds_read_b32 v48, v140
	v_pk_mul_f32 v[46:47], v[46:47], v[60:61]
	s_waitcnt lgkmcnt(0)
	v_pk_mul_f32 v[60:61], v[206:207], v[48:49] op_sel_hi:[1,0]
	v_pk_mul_f32 v[62:63], v[208:209], v[48:49] op_sel_hi:[1,0]
	s_waitcnt vmcnt(0)
	v_pk_fma_f32 v[64:65], v[30:31], v[60:61], v[8:9]
	v_pk_fma_f32 v[60:61], v[32:33], v[62:63], v[6:7]
	v_pk_mul_f32 v[62:63], v[202:203], v[48:49] op_sel_hi:[1,0]
	v_pk_mul_f32 v[48:49], v[204:205], v[48:49] op_sel_hi:[1,0]
	v_pk_fma_f32 v[76:77], v[44:45], v[62:63], v[4:5]
	v_pk_fma_f32 v[48:49], v[46:47], v[48:49], v[2:3]
	v_cvt_pk_bf16_f32 v60, v60, v61
	v_cvt_pk_bf16_f32 v61, v64, v65
	s_nop 0
	v_cvt_pk_bf16_f32 v62, v48, v49
	v_cvt_pk_bf16_f32 v63, v76, v77
	ds_read_b32 v48, v140 offset:64
	global_store_dwordx4 v[130:131], v[60:63], off offset:256 sc0 sc1
	s_waitcnt lgkmcnt(0)
	s_nop 0
	v_pk_mul_f32 v[60:61], v[104:105], v[48:49] op_sel_hi:[1,0]
	v_pk_mul_f32 v[62:63], v[102:103], v[48:49] op_sel_hi:[1,0]
	v_pk_fma_f32 v[64:65], v[30:31], v[60:61], v[8:9]
	v_pk_fma_f32 v[60:61], v[32:33], v[62:63], v[6:7]
	v_pk_mul_f32 v[62:63], v[100:101], v[48:49] op_sel_hi:[1,0]
	v_pk_mul_f32 v[48:49], v[98:99], v[48:49] op_sel_hi:[1,0]
	v_pk_fma_f32 v[76:77], v[44:45], v[62:63], v[4:5]
	v_pk_fma_f32 v[48:49], v[46:47], v[48:49], v[2:3]
	v_cvt_pk_bf16_f32 v60, v60, v61
	v_cvt_pk_bf16_f32 v61, v64, v65
	s_nop 0
	v_cvt_pk_bf16_f32 v62, v48, v49
	v_cvt_pk_bf16_f32 v63, v76, v77
	ds_read_b32 v48, v140 offset:128
	global_store_dwordx4 v[106:107], v[60:63], off offset:256 sc0 sc1
	s_waitcnt lgkmcnt(0)
; __device__ __forceinline__ unsigned cvt_pk_bf16(float lo, float hi) { unsigned r; asm volatile("v_cvt_pk_bf16_f32 %0, %1, %2" : "=v"(r) : "v"(lo), "v"(hi)); return r; }
;     __device__ __forceinline__ void fuse_tail(f32x4 (&acc)[2][2][4][2], const float (&ssq)[2][4], const Unit& u, int wr, int wc, int fr, int fq, int mi, int row0, int col0) const {
;     ...
;         bf16_t* XN = (bf16_t*)((char*)X + RN_DXN);
;         const float* sh = mods_l + nsh_off + (size_t)mi * MODW + col0;
; #pragma unroll
;         for (int bj = 0; bj < 2; ++bj) { f32x4 GG[2], SS[2];
; #pragma unroll
;             for (int n = 0; n < 2; ++n) { GG[n] = *(const f32x4*)(ng + col0 + bj * HALF + 4 * n) * (*(const f32x4*)(sh + D + bj * HALF + 4 * n) + 1.f); SS[n] = *(const f32x4*)(sh + bj * HALF + 4 * n); }
; #pragma unroll
;             for (int ai = 0; ai < 2; ++ai)
; #pragma unroll
;                 for (int m = 0; m < 4; ++m) { const float rstd = S[ai * HALF + wr * 64 + m * 16 + fr];
;                     const f32x4 h0 = acc[ai][bj][m][0] * rstd * GG[0] + SS[0], h1 = acc[ai][bj][m][1] * rstd * GG[1] + SS[1];
;                     u32x4 w; w.x = cvt_pk_bf16(h0[0], h0[1]); w.y = cvt_pk_bf16(h0[2], h0[3]); w.z = cvt_pk_bf16(h1[0], h1[1]); w.w = cvt_pk_bf16(h1[2], h1[3]);
;                     *(u32x4*)(XN + (size_t)(row0 + ai * HALF + m * 16) * D + col0 + bj * HALF) = w; } }
	s_nop 0
	v_pk_mul_f32 v[60:61], v[88:89], v[48:49] op_sel_hi:[1,0]
	v_pk_mul_f32 v[62:63], v[86:87], v[48:49] op_sel_hi:[1,0]
	v_pk_fma_f32 v[64:65], v[30:31], v[60:61], v[8:9]
	v_pk_fma_f32 v[60:61], v[32:33], v[62:63], v[6:7]
	v_pk_mul_f32 v[62:63], v[84:85], v[48:49] op_sel_hi:[1,0]
	v_pk_mul_f32 v[48:49], v[82:83], v[48:49] op_sel_hi:[1,0]
	v_pk_fma_f32 v[76:77], v[44:45], v[62:63], v[4:5]
	v_pk_fma_f32 v[48:49], v[46:47], v[48:49], v[2:3]
	v_cvt_pk_bf16_f32 v60, v60, v61
	v_cvt_pk_bf16_f32 v61, v64, v65
	s_nop 0
	v_cvt_pk_bf16_f32 v62, v48, v49
	v_cvt_pk_bf16_f32 v63, v76, v77
	ds_read_b32 v48, v140 offset:192
	global_store_dwordx4 v[90:91], v[60:63], off offset:256 sc0 sc1
	s_waitcnt lgkmcnt(0)
	s_nop 0
	v_pk_mul_f32 v[60:61], v[72:73], v[48:49] op_sel_hi:[1,0]
	v_pk_mul_f32 v[62:63], v[70:71], v[48:49] op_sel_hi:[1,0]
	v_pk_fma_f32 v[64:65], v[30:31], v[60:61], v[8:9]
	v_pk_fma_f32 v[60:61], v[32:33], v[62:63], v[6:7]
	v_pk_mul_f32 v[62:63], v[68:69], v[48:49] op_sel_hi:[1,0]
	v_pk_mul_f32 v[48:49], v[66:67], v[48:49] op_sel_hi:[1,0]
	v_pk_fma_f32 v[66:67], v[44:45], v[62:63], v[4:5]
	v_pk_fma_f32 v[48:49], v[46:47], v[48:49], v[2:3]
	v_cvt_pk_bf16_f32 v60, v60, v61
	v_cvt_pk_bf16_f32 v61, v64, v65
	s_nop 0
	v_cvt_pk_bf16_f32 v62, v48, v49
	v_cvt_pk_bf16_f32 v63, v66, v67
	ds_read_b32 v48, v140 offset:512
	global_store_dwordx4 v[74:75], v[60:63], off offset:256 sc0 sc1
	s_waitcnt lgkmcnt(0)
	v_pk_mul_f32 v[56:57], v[56:57], v[48:49] op_sel_hi:[1,0]
	v_pk_mul_f32 v[54:55], v[54:55], v[48:49] op_sel_hi:[1,0]
	v_pk_mul_f32 v[52:53], v[52:53], v[48:49] op_sel_hi:[1,0]
	v_pk_mul_f32 v[48:49], v[50:51], v[48:49] op_sel_hi:[1,0]
	v_pk_fma_f32 v[54:55], v[32:33], v[54:55], v[6:7]
	v_pk_fma_f32 v[50:51], v[46:47], v[48:49], v[2:3]
	v_cvt_pk_bf16_f32 v48, v54, v55
	v_pk_fma_f32 v[56:57], v[30:31], v[56:57], v[8:9]
	v_pk_fma_f32 v[52:53], v[44:45], v[52:53], v[4:5]
	v_cvt_pk_bf16_f32 v49, v56, v57
	v_cvt_pk_bf16_f32 v50, v50, v51
	s_nop 0
	v_cvt_pk_bf16_f32 v51, v52, v53
	global_store_dwordx4 v[58:59], v[48:51], off offset:256 sc0 sc1
	ds_read_b32 v48, v140 offset:576
	s_waitcnt lgkmcnt(0)
	v_pk_mul_f32 v[38:39], v[38:39], v[48:49] op_sel_hi:[1,0]
	v_pk_mul_f32 v[36:37], v[36:37], v[48:49] op_sel_hi:[1,0]
	v_pk_mul_f32 v[34:35], v[34:35], v[48:49] op_sel_hi:[1,0]
	v_pk_mul_f32 v[40:41], v[40:41], v[48:49] op_sel_hi:[1,0]
	v_pk_fma_f32 v[38:39], v[32:33], v[38:39], v[6:7]
	v_pk_fma_f32 v[48:49], v[44:45], v[36:37], v[4:5]
	v_pk_fma_f32 v[36:37], v[46:47], v[34:35], v[2:3]
	v_cvt_pk_bf16_f32 v34, v38, v39
	v_pk_fma_f32 v[40:41], v[30:31], v[40:41], v[8:9]
	s_nop 0
	v_cvt_pk_bf16_f32 v35, v40, v41
	v_cvt_pk_bf16_f32 v36, v36, v37
	v_cvt_pk_bf16_f32 v37, v48, v49
	global_store_dwordx4 v[42:43], v[34:37], off offset:256 sc0 sc1
	ds_read_b32 v34, v140 offset:640
	s_waitcnt lgkmcnt(0)
	v_pk_mul_f32 v[22:23], v[22:23], v[34:35] op_sel_hi:[1,0]
	v_pk_mul_f32 v[20:21], v[20:21], v[34:35] op_sel_hi:[1,0]
	v_pk_mul_f32 v[18:19], v[18:19], v[34:35] op_sel_hi:[1,0]
	v_pk_mul_f32 v[24:25], v[24:25], v[34:35] op_sel_hi:[1,0]
	v_pk_fma_f32 v[22:23], v[32:33], v[22:23], v[6:7]
	v_pk_fma_f32 v[34:35], v[44:45], v[20:21], v[4:5]
	v_pk_fma_f32 v[20:21], v[46:47], v[18:19], v[2:3]
	v_cvt_pk_bf16_f32 v18, v22, v23
	v_pk_fma_f32 v[24:25], v[30:31], v[24:25], v[8:9]
	s_nop 0
	v_cvt_pk_bf16_f32 v19, v24, v25
	v_cvt_pk_bf16_f32 v20, v20, v21
	v_cvt_pk_bf16_f32 v21, v34, v35
	global_store_dwordx4 v[26:27], v[18:21], off offset:256 sc0 sc1
	ds_read_b32 v18, v140 offset:704
	s_waitcnt lgkmcnt(0)
	v_pk_mul_f32 v[12:13], v[12:13], v[18:19] op_sel_hi:[1,0]
	s_nop 0
	v_pk_fma_f32 v[8:9], v[30:31], v[12:13], v[8:9]
	v_pk_mul_f32 v[10:11], v[10:11], v[18:19] op_sel_hi:[1,0]
	v_pk_mul_f32 v[12:13], v[14:15], v[18:19] op_sel_hi:[1,0]
	v_pk_mul_f32 v[16:17], v[16:17], v[18:19] op_sel_hi:[1,0]
	v_pk_fma_f32 v[10:11], v[44:45], v[10:11], v[4:5]
	v_pk_fma_f32 v[4:5], v[46:47], v[12:13], v[2:3]
	v_pk_fma_f32 v[6:7], v[32:33], v[16:17], v[6:7]
	s_nop 0
	v_cvt_pk_bf16_f32 v2, v6, v7
	v_cvt_pk_bf16_f32 v3, v8, v9
	v_cvt_pk_bf16_f32 v4, v4, v5
	v_cvt_pk_bf16_f32 v5, v10, v11
	global_store_dwordx4 v[28:29], v[2:5], off offset:256 sc0 sc1
	s_and_b64 vcc, exec, s[38:39]
	s_mov_b64 s[34:35], -1
	s_cbranch_vccnz .LBB9_1129

; __device__ __forceinline__ unsigned cvt_pk_bf16(float lo, float hi) { unsigned r; asm volatile("v_cvt_pk_bf16_f32 %0, %1, %2" : "=v"(r) : "v"(lo), "v"(hi)); return r; }
;     __device__ __forceinline__ void operator()(f32x4 (&acc)[2][2][4][2], const Unit& u, int wr, int wc, int fr, int fq) const {
;         if (u.sw) {
;             bf16_t* base = (bf16_t*)slab + (size_t)(((u.pm - 32) * 8 + u.pn) * 8 + u.ks) * 65536 + (size_t)(wr * 64 + fr) * 256 + wc * 32 + 8 * fq;
; #pragma unroll
;             for (int ai = 0; ai < 2; ++ai)
; #pragma unroll
;                 for (int m = 0; m < 4; ++m)
; #pragma unroll
;                     for (int bj = 0; bj < 2; ++bj) { const f32x4 v0 = acc[ai][bj][m][0], v1 = acc[ai][bj][m][1];
;                         u32x4 w; w.x = cvt_pk_bf16(v0[0], v0[1]); w.y = cvt_pk_bf16(v0[2], v0[3]); w.z = cvt_pk_bf16(v1[0], v1[1]); w.w = cvt_pk_bf16(v1[2], v1[3]);
;                         *(u32x4*)(base + (size_t)(ai * HALF + m * 16) * 256 + bj * HALF) = w; }
;             return;
.LBB9_1228:
	v_mov_b32_e32 v185, v0
	s_nop 0
	v_readfirstlane_b32 s4, v185
	s_ashr_i32 s34, s4, 8
	s_bfe_u32 s35, s4, 0x20006
	v_and_b32_e32 v184, 15, v185
	s_cmp_eq_u32 s47, 0
	v_bfe_u32 v190, v185, 4, 2
	s_cbranch_scc1 .LBB9_1268
	s_lshl_b32 s1, s46, 3
	s_lshl_b32 s0, s65, 6
	s_add_i32 s1, s5, s1
	s_add_i32 s0, s1, s0
	s_addk_i32 s0, 0xf800
	s_ashr_i32 s1, s0, 31
	s_lshl_b64 s[0:1], s[0:1], 17
	v_lshl_or_b32 v130, s34, 6, v184
	s_add_u32 s0, s75, s0
	v_ashrrev_i32_e32 v131, 31, v130
	s_addc_u32 s1, s76, s1
	v_lshlrev_b64 v[130:131], 9, v[130:131]
	v_lshl_add_u64 v[130:131], s[0:1], 0, v[130:131]
	s_lshl_b32 s48, s35, 6
	v_lshl_add_u64 v[130:131], v[130:131], 0, s[48:49]
	v_lshlrev_b32_e32 v186, 4, v190
	v_lshl_add_u64 v[130:131], v[130:131], 0, v[186:187]
	v_cvt_pk_bf16_f32 v132, v126, v127
	v_cvt_pk_bf16_f32 v133, v128, v129
	v_cvt_pk_bf16_f32 v134, v122, v123
	v_cvt_pk_bf16_f32 v135, v124, v125
	global_store_dwordx4 v[130:131], v[132:135], off sc0 sc1
	v_add_co_u32_e32 v136, vcc, s28, v130
	s_nop 0
	v_cvt_pk_bf16_f32 v132, v118, v119
	v_cvt_pk_bf16_f32 v133, v120, v121
	v_cvt_pk_bf16_f32 v134, v114, v115
	v_cvt_pk_bf16_f32 v135, v116, v117
	global_store_dwordx4 v[130:131], v[132:135], off offset:256 sc0 sc1
	v_addc_co_u32_e32 v137, vcc, 0, v131, vcc
	s_nop 0
	v_cvt_pk_bf16_f32 v132, v110, v111
	v_cvt_pk_bf16_f32 v133, v112, v113
	v_cvt_pk_bf16_f32 v134, v106, v107
	v_cvt_pk_bf16_f32 v135, v108, v109
	s_movk_i32 s0, 0x4000
	global_store_dwordx4 v[136:137], v[132:135], off sc0 sc1
	s_nop 1
	v_cvt_pk_bf16_f32 v132, v102, v103
	v_cvt_pk_bf16_f32 v133, v104, v105
	v_cvt_pk_bf16_f32 v134, v98, v99
	v_cvt_pk_bf16_f32 v135, v100, v101
	global_store_dwordx4 v[136:137], v[132:135], off offset:256 sc0 sc1
	v_add_co_u32_e32 v136, vcc, s0, v130
	s_nop 0
	v_cvt_pk_bf16_f32 v132, v94, v95
	v_cvt_pk_bf16_f32 v133, v96, v97
	v_cvt_pk_bf16_f32 v134, v90, v91
	v_cvt_pk_bf16_f32 v135, v92, v93
	s_nop 0
	v_addc_co_u32_e32 v137, vcc, 0, v131, vcc
	s_movk_i32 s0, 0x6000
	global_store_dwordx4 v[136:137], v[132:135], off sc0 sc1
	s_nop 1
	v_cvt_pk_bf16_f32 v132, v86, v87
	v_cvt_pk_bf16_f32 v133, v88, v89
	v_cvt_pk_bf16_f32 v134, v78, v79
	v_cvt_pk_bf16_f32 v135, v80, v81
	global_store_dwordx4 v[136:137], v[132:135], off offset:256 sc0 sc1
	v_add_co_u32_e32 v136, vcc, s0, v130
	s_nop 0
	v_cvt_pk_bf16_f32 v132, v82, v83
	v_cvt_pk_bf16_f32 v133, v84, v85
	v_cvt_pk_bf16_f32 v134, v74, v75
	v_cvt_pk_bf16_f32 v135, v76, v77
	s_nop 0
	v_addc_co_u32_e32 v137, vcc, 0, v131, vcc
	global_store_dwordx4 v[136:137], v[132:135], off sc0 sc1
	s_mov_b32 s0, 0x12000
	s_nop 0
	v_cvt_pk_bf16_f32 v132, v70, v71
	v_cvt_pk_bf16_f32 v133, v72, v73
	v_cvt_pk_bf16_f32 v134, v66, v67
	v_cvt_pk_bf16_f32 v135, v68, v69
	global_store_dwordx4 v[136:137], v[132:135], off offset:256 sc0 sc1
	v_add_co_u32_e32 v136, vcc, s59, v130
	s_nop 0
	v_cvt_pk_bf16_f32 v132, v62, v63
	v_cvt_pk_bf16_f32 v133, v64, v65
	v_cvt_pk_bf16_f32 v134, v58, v59
	v_cvt_pk_bf16_f32 v135, v60, v61
	s_nop 0
	v_addc_co_u32_e32 v137, vcc, 0, v131, vcc
	global_store_dwordx4 v[136:137], v[132:135], off sc0 sc1
	s_nop 1
	v_cvt_pk_bf16_f32 v132, v54, v55
	v_cvt_pk_bf16_f32 v133, v56, v57
	v_cvt_pk_bf16_f32 v134, v46, v47
	v_cvt_pk_bf16_f32 v135, v48, v49
	global_store_dwordx4 v[136:137], v[132:135], off offset:256 sc0 sc1
	v_add_co_u32_e32 v136, vcc, s0, v130
	s_nop 0
	v_cvt_pk_bf16_f32 v132, v50, v51
	v_cvt_pk_bf16_f32 v133, v52, v53
	v_cvt_pk_bf16_f32 v134, v42, v43
	v_cvt_pk_bf16_f32 v135, v44, v45
	s_nop 0
	v_addc_co_u32_e32 v137, vcc, 0, v131, vcc
	s_mov_b32 s0, 0x14000
	global_store_dwordx4 v[136:137], v[132:135], off sc0 sc1
	s_nop 1
	v_cvt_pk_bf16_f32 v132, v38, v39
	v_cvt_pk_bf16_f32 v133, v40, v41
	v_cvt_pk_bf16_f32 v134, v34, v35
	v_cvt_pk_bf16_f32 v135, v36, v37
	global_store_dwordx4 v[136:137], v[132:135], off offset:256 sc0 sc1
	v_add_co_u32_e32 v136, vcc, s0, v130
	s_nop 0
	v_cvt_pk_bf16_f32 v132, v30, v31
	v_cvt_pk_bf16_f32 v133, v32, v33
	v_cvt_pk_bf16_f32 v134, v26, v27
	v_cvt_pk_bf16_f32 v135, v28, v29
	s_nop 0
	v_addc_co_u32_e32 v137, vcc, 0, v131, vcc
	s_mov_b32 s0, 0x16000
	global_store_dwordx4 v[136:137], v[132:135], off sc0 sc1
	s_nop 1
	v_cvt_pk_bf16_f32 v132, v22, v23
	v_cvt_pk_bf16_f32 v133, v24, v25
	v_cvt_pk_bf16_f32 v134, v14, v15
	v_cvt_pk_bf16_f32 v135, v16, v17
	global_store_dwordx4 v[136:137], v[132:135], off offset:256 sc0 sc1
	v_add_co_u32_e32 v136, vcc, s0, v130
	s_nop 0
	v_cvt_pk_bf16_f32 v132, v18, v19
	v_cvt_pk_bf16_f32 v133, v20, v21
	s_nop 0
	v_addc_co_u32_e32 v137, vcc, 0, v131, vcc
	v_cvt_pk_bf16_f32 v134, v10, v11
	v_cvt_pk_bf16_f32 v135, v12, v13
	global_store_dwordx4 v[136:137], v[132:135], off sc0 sc1
	v_cvt_pk_bf16_f32 v130, v6, v7
	v_cvt_pk_bf16_f32 v131, v8, v9
	s_nop 1
	v_cvt_pk_bf16_f32 v132, v2, v3
	v_cvt_pk_bf16_f32 v133, v4, v5
	global_store_dwordx4 v[136:137], v[130:133], off offset:256 sc0 sc1
	s_cbranch_execnz .LBB9_1269
; __device__ __forceinline__ unsigned cvt_pk_bf16(float lo, float hi) { unsigned r; asm volatile("v_cvt_pk_bf16_f32 %0, %1, %2" : "=v"(r) : "v"(lo), "v"(hi)); return r; }
;     __device__ __forceinline__ void operator()(f32x4 (&acc)[2][2][4][2], const Unit& u, int wr, int wc, int fr, int fq) const {
;     ...
;         if (XF32) {
; #pragma unroll
;             for (int am = 0; am < 4; ++am) { const int ai = am >> 1, m0 = (am & 1) * 2;
;                 f32x4 xf[2][2][2];
; #pragma unroll
;                 for (int mm = 0; mm < 2; ++mm)
; #pragma unroll
;                     for (int bj = 0; bj < 2; ++bj)
; #pragma unroll
;                         for (int n = 0; n < 2; ++n) xf[mm][bj][n] = *(const f32x4*)(xin + (size_t)(row0 + ai * HALF + (m0 + mm) * 16) * D + col0 + bj * HALF + 4 * n);
;                 __builtin_amdgcn_sched_barrier(0);
; #pragma unroll
;                 for (int mm = 0; mm < 2; ++mm)
; #pragma unroll
;                     for (int bj = 0; bj < 2; ++bj) { const f32x4 v0 = xf[mm][bj][0] + gv[bj][0] * acc[ai][bj][m0 + mm][0], v1 = xf[mm][bj][1] + gv[bj][1] * acc[ai][bj][m0 + mm][1];
;                         if (FUSE) { acc[ai][bj][m0 + mm][0] = v0; acc[ai][bj][m0 + mm][1] = v1; ssq[ai][m0 + mm] += ((v0[0] * v0[0] + v0[1] * v0[1]) + (v0[2] * v0[2] + v0[3] * v0[3])) + ((v1[0] * v1[0] + v1[1] * v1[1]) + (v1[2] * v1[2] + v1[3] * v1[3])); }
;                         u32x4 w; w.x = cvt_pk_bf16(v0[0], v0[1]); w.y = cvt_pk_bf16(v0[2], v0[3]); w.z = cvt_pk_bf16(v1[0], v1[1]); w.w = cvt_pk_bf16(v1[2], v1[3]);
;                         *(u32x4*)(X + (size_t)(row0 + ai * HALF + (m0 + mm) * 16) * D + col0 + bj * HALF) = w; }
.LBB9_1230:
	s_lshl_b32 s47, s65, 8
	s_lshl_b32 s0, s34, 6
	s_add_i32 s3, s0, s47
	s_lshl_b32 s0, s46, 8
	s_lshl_b32 s1, s35, 5
	s_or_b32 s0, s1, s0
	v_lshl_or_b32 v176, v190, 3, s0
	s_min_i32 s0, s65, 32
	s_ashr_i32 s0, s0, 3
	s_mul_i32 s48, s0, 0xc000
	s_mul_hi_i32 s5, s0, 0xc000
	s_add_u32 s0, s96, s48
	v_ashrrev_i32_e32 v177, 31, v176
	s_addc_u32 s1, s93, s5
	v_lshlrev_b64 v[178:179], 2, v[176:177]
	v_lshl_add_u64 v[130:131], s[0:1], 0, v[178:179]
	s_mov_b64 s[0:1], 0x104000
	v_or_b32_e32 v174, s3, v184
	v_lshl_add_u64 v[134:135], v[130:131], 0, s[0:1]
	s_mov_b32 s0, 0x104000
	v_ashrrev_i32_e32 v175, 31, v174
	v_add_co_u32_e32 v130, vcc, s0, v130
	v_lshl_add_u64 v[172:173], s[10:11], 0, v[178:179]
	v_lshlrev_b64 v[158:159], 13, v[174:175]
	v_or_b32_e32 v216, 16, v174
	v_addc_co_u32_e32 v131, vcc, 0, v131, vcc
	v_lshl_add_u64 v[158:159], v[172:173], 0, v[158:159]
	v_ashrrev_i32_e32 v217, 31, v216
	global_load_dwordx4 v[142:145], v[130:131], off
	s_nop 0
	global_load_dwordx4 v[130:133], v[134:135], off offset:528
	global_load_dwordx4 v[138:141], v[134:135], off offset:16
	s_nop 0
	global_load_dwordx4 v[134:137], v[134:135], off offset:512
	s_nop 0
	global_load_dwordx4 v[164:167], v[158:159], off offset:16
	global_load_dwordx4 v[168:171], v[158:159], off
	global_load_dwordx4 v[192:195], v[158:159], off offset:528
	global_load_dwordx4 v[196:199], v[158:159], off offset:512
	v_lshlrev_b64 v[158:159], 13, v[216:217]
	v_lshl_add_u64 v[158:159], v[172:173], 0, v[158:159]
	global_load_dwordx4 v[200:203], v[158:159], off offset:16
	global_load_dwordx4 v[204:207], v[158:159], off
	global_load_dwordx4 v[208:211], v[158:159], off offset:528
	global_load_dwordx4 v[212:215], v[158:159], off offset:512
	s_waitcnt vmcnt(0)
	v_pk_fma_f32 v[160:161], v[128:129], v[144:145], v[170:171]
	v_pk_fma_f32 v[162:163], v[126:127], v[142:143], v[168:169]
	v_pk_fma_f32 v[128:129], v[122:123], v[138:139], v[164:165]
	v_mul_f32_e32 v122, v163, v163
	v_mul_f32_e32 v123, v161, v161
	v_pk_fma_f32 v[126:127], v[124:125], v[140:141], v[166:167]
	v_fmac_f32_e32 v122, v162, v162
	v_fmac_f32_e32 v123, v160, v160
	v_add_f32_e32 v122, v122, v123
	v_mul_f32_e32 v123, v129, v129
	v_mul_f32_e32 v124, v127, v127
	v_lshlrev_b64 v[158:159], 12, v[174:175]
	v_fmac_f32_e32 v123, v128, v128
	v_fmac_f32_e32 v124, v126, v126
	v_add_f32_e32 v123, v123, v124
	v_lshl_add_u64 v[164:165], s[42:43], 0, v[158:159]
	v_lshlrev_b64 v[180:181], 1, v[176:177]
	v_add_f32_e32 v166, v122, v123
	v_cvt_pk_bf16_f32 v122, v162, v163
	v_cvt_pk_bf16_f32 v123, v160, v161
	v_lshl_add_u64 v[164:165], v[164:165], 0, v[180:181]
	v_pk_fma_f32 v[120:121], v[120:121], v[136:137], v[198:199]
	v_pk_fma_f32 v[118:119], v[118:119], v[134:135], v[196:197]
	v_cvt_pk_bf16_f32 v124, v128, v129
	v_cvt_pk_bf16_f32 v125, v126, v127
	global_store_dwordx4 v[164:165], v[122:125], off sc0 sc1
	v_pk_fma_f32 v[116:117], v[116:117], v[132:133], v[194:195]
	v_pk_fma_f32 v[114:115], v[114:115], v[130:131], v[192:193]
	v_mul_f32_e32 v122, v119, v119
	v_mul_f32_e32 v123, v121, v121
	v_fmac_f32_e32 v122, v118, v118
	v_fmac_f32_e32 v123, v120, v120
	v_add_f32_e32 v122, v122, v123
	v_mul_f32_e32 v123, v115, v115
	v_mul_f32_e32 v124, v117, v117
	v_fmac_f32_e32 v123, v114, v114
	v_fmac_f32_e32 v124, v116, v116
	v_add_f32_e32 v123, v123, v124
	v_add_f32_e32 v122, v122, v123
	v_add_f32_e32 v186, v166, v122
	v_cvt_pk_bf16_f32 v122, v118, v119
	v_cvt_pk_bf16_f32 v123, v120, v121
	v_cvt_pk_bf16_f32 v124, v114, v115
	v_cvt_pk_bf16_f32 v125, v116, v117
	global_store_dwordx4 v[164:165], v[122:125], off offset:256 sc0 sc1
	v_pk_fma_f32 v[112:113], v[112:113], v[144:145], v[206:207]
	v_pk_fma_f32 v[108:109], v[108:109], v[140:141], v[202:203]
	v_lshlrev_b64 v[122:123], 12, v[216:217]
	v_pk_fma_f32 v[124:125], v[110:111], v[142:143], v[204:205]
	v_pk_fma_f32 v[110:111], v[106:107], v[138:139], v[200:201]
	v_lshl_add_u64 v[106:107], s[42:43], 0, v[122:123]
	v_cvt_pk_bf16_f32 v164, v124, v125
	v_cvt_pk_bf16_f32 v165, v112, v113
	v_cvt_pk_bf16_f32 v166, v110, v111
	v_cvt_pk_bf16_f32 v167, v108, v109
	v_lshl_add_u64 v[106:107], v[106:107], 0, v[180:181]
	v_pk_fma_f32 v[104:105], v[104:105], v[136:137], v[214:215]
	v_pk_fma_f32 v[102:103], v[102:103], v[134:135], v[212:213]
	v_pk_fma_f32 v[100:101], v[100:101], v[132:133], v[210:211]
	v_pk_fma_f32 v[98:99], v[98:99], v[130:131], v[208:209]
	global_store_dwordx4 v[106:107], v[164:167], off sc0 sc1
	s_nop 1
	v_cvt_pk_bf16_f32 v164, v102, v103
	v_cvt_pk_bf16_f32 v165, v104, v105
	v_cvt_pk_bf16_f32 v166, v98, v99
	v_cvt_pk_bf16_f32 v167, v100, v101
	global_store_dwordx4 v[106:107], v[164:167], off offset:256 sc0 sc1
	v_or_b32_e32 v106, 32, v174
	v_ashrrev_i32_e32 v107, 31, v106
	v_lshlrev_b64 v[164:165], 13, v[106:107]
	v_or_b32_e32 v220, 48, v174
	v_lshl_add_u64 v[164:165], v[172:173], 0, v[164:165]
	v_ashrrev_i32_e32 v221, 31, v220
	global_load_dwordx4 v[168:171], v[164:165], off offset:16
	global_load_dwordx4 v[192:195], v[164:165], off
	global_load_dwordx4 v[196:199], v[164:165], off offset:528
	global_load_dwordx4 v[200:203], v[164:165], off offset:512
	v_lshlrev_b64 v[164:165], 13, v[220:221]
	v_lshl_add_u64 v[164:165], v[172:173], 0, v[164:165]
	global_load_dwordx4 v[204:207], v[164:165], off offset:16
	global_load_dwordx4 v[208:211], v[164:165], off
	global_load_dwordx4 v[212:215], v[164:165], off offset:528
	global_load_dwordx4 v[216:219], v[164:165], off offset:512
	v_lshlrev_b64 v[106:107], 12, v[106:107]
	s_waitcnt vmcnt(6)
; __device__ __forceinline__ unsigned cvt_pk_bf16(float lo, float hi) { unsigned r; asm volatile("v_cvt_pk_bf16_f32 %0, %1, %2" : "=v"(r) : "v"(lo), "v"(hi)); return r; }
;     __device__ __forceinline__ void operator()(f32x4 (&acc)[2][2][4][2], const Unit& u, int wr, int wc, int fr, int fq) const {
;     ...
;         if (XF32) {
; #pragma unroll
;             for (int am = 0; am < 4; ++am) { const int ai = am >> 1, m0 = (am & 1) * 2;
;                 f32x4 xf[2][2][2];
; #pragma unroll
;                 for (int mm = 0; mm < 2; ++mm)
; #pragma unroll
;                     for (int bj = 0; bj < 2; ++bj)
; #pragma unroll
;                         for (int n = 0; n < 2; ++n) xf[mm][bj][n] = *(const f32x4*)(xin + (size_t)(row0 + ai * HALF + (m0 + mm) * 16) * D + col0 + bj * HALF + 4 * n);
;                 __builtin_amdgcn_sched_barrier(0);
; #pragma unroll
;                 for (int mm = 0; mm < 2; ++mm)
; #pragma unroll
;                     for (int bj = 0; bj < 2; ++bj) { const f32x4 v0 = xf[mm][bj][0] + gv[bj][0] * acc[ai][bj][m0 + mm][0], v1 = xf[mm][bj][1] + gv[bj][1] * acc[ai][bj][m0 + mm][1];
;                         if (FUSE) { acc[ai][bj][m0 + mm][0] = v0; acc[ai][bj][m0 + mm][1] = v1; ssq[ai][m0 + mm] += ((v0[0] * v0[0] + v0[1] * v0[1]) + (v0[2] * v0[2] + v0[3] * v0[3])) + ((v1[0] * v1[0] + v1[1] * v1[1]) + (v1[2] * v1[2] + v1[3] * v1[3])); }
;                         u32x4 w; w.x = cvt_pk_bf16(v0[0], v0[1]); w.y = cvt_pk_bf16(v0[2], v0[3]); w.z = cvt_pk_bf16(v1[0], v1[1]); w.w = cvt_pk_bf16(v1[2], v1[3]);
;                         *(u32x4*)(X + (size_t)(row0 + ai * HALF + (m0 + mm) * 16) * D + col0 + bj * HALF) = w; }
	v_pk_fma_f32 v[166:167], v[94:95], v[142:143], v[192:193]
	v_pk_fma_f32 v[94:95], v[90:91], v[138:139], v[168:169]
	v_lshl_add_u64 v[90:91], s[42:43], 0, v[106:107]
	v_pk_fma_f32 v[164:165], v[96:97], v[144:145], v[194:195]
	v_pk_fma_f32 v[92:93], v[92:93], v[140:141], v[170:171]
	v_cvt_pk_bf16_f32 v168, v166, v167
	v_cvt_pk_bf16_f32 v169, v164, v165
	v_cvt_pk_bf16_f32 v170, v94, v95
	v_lshl_add_u64 v[90:91], v[90:91], 0, v[180:181]
	v_cvt_pk_bf16_f32 v171, v92, v93
	global_store_dwordx4 v[90:91], v[168:171], off sc0 sc1
	s_waitcnt vmcnt(5)
	v_pk_fma_f32 v[88:89], v[88:89], v[136:137], v[202:203]
	v_pk_fma_f32 v[86:87], v[86:87], v[134:135], v[200:201]
	v_pk_fma_f32 v[80:81], v[80:81], v[132:133], v[198:199]
	v_pk_fma_f32 v[78:79], v[78:79], v[130:131], v[196:197]
	v_cvt_pk_bf16_f32 v168, v86, v87
	v_cvt_pk_bf16_f32 v169, v88, v89
	s_waitcnt vmcnt(3)
	v_pk_fma_f32 v[96:97], v[82:83], v[142:143], v[208:209]
	v_cvt_pk_bf16_f32 v170, v78, v79
	v_cvt_pk_bf16_f32 v171, v80, v81
	global_store_dwordx4 v[90:91], v[168:171], off offset:256 sc0 sc1
	v_lshlrev_b64 v[90:91], 12, v[220:221]
	v_pk_fma_f32 v[82:83], v[74:75], v[138:139], v[204:205]
	v_lshl_add_u64 v[74:75], s[42:43], 0, v[90:91]
	v_pk_fma_f32 v[84:85], v[84:85], v[144:145], v[210:211]
	v_pk_fma_f32 v[76:77], v[76:77], v[140:141], v[206:207]
	v_cvt_pk_bf16_f32 v168, v96, v97
	v_cvt_pk_bf16_f32 v169, v84, v85
	v_cvt_pk_bf16_f32 v170, v82, v83
	v_lshl_add_u64 v[74:75], v[74:75], 0, v[180:181]
	v_cvt_pk_bf16_f32 v171, v76, v77
	s_waitcnt vmcnt(2)
	v_pk_fma_f32 v[72:73], v[72:73], v[136:137], v[218:219]
	v_pk_fma_f32 v[70:71], v[70:71], v[134:135], v[216:217]
	v_pk_fma_f32 v[68:69], v[68:69], v[132:133], v[214:215]
	v_pk_fma_f32 v[66:67], v[66:67], v[130:131], v[212:213]
	global_store_dwordx4 v[74:75], v[168:171], off sc0 sc1
	s_nop 1
	v_cvt_pk_bf16_f32 v168, v70, v71
	v_cvt_pk_bf16_f32 v169, v72, v73
	v_cvt_pk_bf16_f32 v170, v66, v67
	v_cvt_pk_bf16_f32 v171, v68, v69
	global_store_dwordx4 v[74:75], v[168:171], off offset:256 sc0 sc1
	v_add_u32_e32 v74, 0x80, v174
	v_ashrrev_i32_e32 v75, 31, v74
	v_lshlrev_b64 v[168:169], 13, v[74:75]
	v_add_u32_e32 v224, 0x90, v174
	v_lshl_add_u64 v[168:169], v[172:173], 0, v[168:169]
	v_ashrrev_i32_e32 v225, 31, v224
	global_load_dwordx4 v[192:195], v[168:169], off offset:16
	global_load_dwordx4 v[196:199], v[168:169], off
	global_load_dwordx4 v[200:203], v[168:169], off offset:528
	global_load_dwordx4 v[204:207], v[168:169], off offset:512
	v_lshlrev_b64 v[168:169], 13, v[224:225]
	v_lshl_add_u64 v[168:169], v[172:173], 0, v[168:169]
	global_load_dwordx4 v[208:211], v[168:169], off offset:16
	global_load_dwordx4 v[212:215], v[168:169], off
	global_load_dwordx4 v[216:219], v[168:169], off offset:528
	global_load_dwordx4 v[220:223], v[168:169], off offset:512
	v_lshlrev_b64 v[74:75], 12, v[74:75]
	s_waitcnt vmcnt(6)
	v_pk_fma_f32 v[170:171], v[62:63], v[142:143], v[196:197]
	v_pk_fma_f32 v[62:63], v[58:59], v[138:139], v[192:193]
	v_lshl_add_u64 v[58:59], s[42:43], 0, v[74:75]
	v_pk_fma_f32 v[168:169], v[64:65], v[144:145], v[198:199]
	v_pk_fma_f32 v[60:61], v[60:61], v[140:141], v[194:195]
	v_cvt_pk_bf16_f32 v192, v170, v171
	v_cvt_pk_bf16_f32 v193, v168, v169
	v_cvt_pk_bf16_f32 v194, v62, v63
	v_lshl_add_u64 v[58:59], v[58:59], 0, v[180:181]
	v_cvt_pk_bf16_f32 v195, v60, v61
	global_store_dwordx4 v[58:59], v[192:195], off sc0 sc1
	s_waitcnt vmcnt(5)
	v_pk_fma_f32 v[56:57], v[56:57], v[136:137], v[206:207]
	v_pk_fma_f32 v[54:55], v[54:55], v[134:135], v[204:205]
	v_pk_fma_f32 v[48:49], v[48:49], v[132:133], v[202:203]
	v_pk_fma_f32 v[46:47], v[46:47], v[130:131], v[200:201]
	v_cvt_pk_bf16_f32 v192, v54, v55
	v_cvt_pk_bf16_f32 v193, v56, v57
	s_waitcnt vmcnt(3)
	v_pk_fma_f32 v[64:65], v[50:51], v[142:143], v[212:213]
	v_cvt_pk_bf16_f32 v194, v46, v47
	v_cvt_pk_bf16_f32 v195, v48, v49
	global_store_dwordx4 v[58:59], v[192:195], off offset:256 sc0 sc1
	v_lshlrev_b64 v[58:59], 12, v[224:225]
	v_pk_fma_f32 v[50:51], v[42:43], v[138:139], v[208:209]
	v_lshl_add_u64 v[42:43], s[42:43], 0, v[58:59]
	v_pk_fma_f32 v[52:53], v[52:53], v[144:145], v[214:215]
	v_pk_fma_f32 v[44:45], v[44:45], v[140:141], v[210:211]
	v_cvt_pk_bf16_f32 v192, v64, v65
	v_cvt_pk_bf16_f32 v193, v52, v53
	v_cvt_pk_bf16_f32 v194, v50, v51
	v_lshl_add_u64 v[42:43], v[42:43], 0, v[180:181]
	v_cvt_pk_bf16_f32 v195, v44, v45
	s_waitcnt vmcnt(2)
; __device__ __forceinline__ unsigned cvt_pk_bf16(float lo, float hi) { unsigned r; asm volatile("v_cvt_pk_bf16_f32 %0, %1, %2" : "=v"(r) : "v"(lo), "v"(hi)); return r; }
;     __device__ __forceinline__ void fuse_tail(f32x4 (&acc)[2][2][4][2], const float (&ssq)[2][4], const Unit& u, int wr, int wc, int fr, int fq, int mi, int row0, int col0) const {
;     ...
;             for (int m = 0; m < 4; ++m) { float t = ssq[ai][m]; t += __shfl_xor(t, 16); t += __shfl_xor(t, 32);
;                 if (fq == 0) P[(ai * HALF + wr * 64 + m * 16 + fr) * 4 + wc] = t; }
;     __device__ __forceinline__ void operator()(f32x4 (&acc)[2][2][4][2], const Unit& u, int wr, int wc, int fr, int fq) const {
;     ...
;                         for (int n = 0; n < 2; ++n) xf[mm][bj][n] = *(const f32x4*)(xin + (size_t)(row0 + ai * HALF + (m0 + mm) * 16) * D + col0 + bj * HALF + 4 * n);
;                 __builtin_amdgcn_sched_barrier(0);
; #pragma unroll
;                 for (int mm = 0; mm < 2; ++mm)
; #pragma unroll
;                     for (int bj = 0; bj < 2; ++bj) { const f32x4 v0 = xf[mm][bj][0] + gv[bj][0] * acc[ai][bj][m0 + mm][0], v1 = xf[mm][bj][1] + gv[bj][1] * acc[ai][bj][m0 + mm][1];
;                         if (FUSE) { acc[ai][bj][m0 + mm][0] = v0; acc[ai][bj][m0 + mm][1] = v1; ssq[ai][m0 + mm] += ((v0[0] * v0[0] + v0[1] * v0[1]) + (v0[2] * v0[2] + v0[3] * v0[3])) + ((v1[0] * v1[0] + v1[1] * v1[1]) + (v1[2] * v1[2] + v1[3] * v1[3])); }
;                         u32x4 w; w.x = cvt_pk_bf16(v0[0], v0[1]); w.y = cvt_pk_bf16(v0[2], v0[3]); w.z = cvt_pk_bf16(v1[0], v1[1]); w.w = cvt_pk_bf16(v1[2], v1[3]);
;                         *(u32x4*)(X + (size_t)(row0 + ai * HALF + (m0 + mm) * 16) * D + col0 + bj * HALF) = w; }
	v_pk_fma_f32 v[40:41], v[40:41], v[136:137], v[222:223]
	v_pk_fma_f32 v[38:39], v[38:39], v[134:135], v[220:221]
	v_pk_fma_f32 v[36:37], v[36:37], v[132:133], v[218:219]
	v_pk_fma_f32 v[34:35], v[34:35], v[130:131], v[216:217]
	global_store_dwordx4 v[42:43], v[192:195], off sc0 sc1
	s_nop 1
	v_cvt_pk_bf16_f32 v192, v38, v39
	v_cvt_pk_bf16_f32 v193, v40, v41
	v_cvt_pk_bf16_f32 v194, v34, v35
	v_cvt_pk_bf16_f32 v195, v36, v37
	global_store_dwordx4 v[42:43], v[192:195], off offset:256 sc0 sc1
	v_add_u32_e32 v42, 0xa0, v174
	v_add_u32_e32 v224, 0xb0, v174
	v_ashrrev_i32_e32 v43, 31, v42
	v_ashrrev_i32_e32 v225, 31, v224
	v_lshlrev_b64 v[192:193], 13, v[42:43]
	v_lshlrev_b64 v[174:175], 13, v[224:225]
	v_lshl_add_u64 v[204:205], v[172:173], 0, v[192:193]
	v_lshl_add_u64 v[172:173], v[172:173], 0, v[174:175]
	global_load_dwordx4 v[192:195], v[204:205], off offset:16
	global_load_dwordx4 v[196:199], v[204:205], off
	global_load_dwordx4 v[200:203], v[204:205], off offset:528
	s_nop 0
	global_load_dwordx4 v[204:207], v[204:205], off offset:512
	s_nop 0
	global_load_dwordx4 v[208:211], v[172:173], off offset:16
	global_load_dwordx4 v[212:215], v[172:173], off
	global_load_dwordx4 v[216:219], v[172:173], off offset:528
	global_load_dwordx4 v[220:223], v[172:173], off offset:512
	v_lshlrev_b64 v[42:43], 12, v[42:43]
	s_waitcnt vmcnt(6)
	v_pk_fma_f32 v[174:175], v[30:31], v[142:143], v[196:197]
	v_pk_fma_f32 v[30:31], v[26:27], v[138:139], v[192:193]
	v_lshl_add_u64 v[26:27], s[42:43], 0, v[42:43]
	v_pk_fma_f32 v[172:173], v[32:33], v[144:145], v[198:199]
	v_pk_fma_f32 v[28:29], v[28:29], v[140:141], v[194:195]
	v_cvt_pk_bf16_f32 v192, v174, v175
	v_cvt_pk_bf16_f32 v193, v172, v173
	v_cvt_pk_bf16_f32 v194, v30, v31
	v_lshl_add_u64 v[26:27], v[26:27], 0, v[180:181]
	v_cvt_pk_bf16_f32 v195, v28, v29
	global_store_dwordx4 v[26:27], v[192:195], off sc0 sc1
	s_waitcnt vmcnt(5)
	v_pk_fma_f32 v[24:25], v[24:25], v[136:137], v[206:207]
	v_pk_fma_f32 v[22:23], v[22:23], v[134:135], v[204:205]
	v_pk_fma_f32 v[16:17], v[16:17], v[132:133], v[202:203]
	v_pk_fma_f32 v[14:15], v[14:15], v[130:131], v[200:201]
	v_cvt_pk_bf16_f32 v192, v22, v23
	v_cvt_pk_bf16_f32 v193, v24, v25
	s_waitcnt vmcnt(3)
	v_pk_fma_f32 v[142:143], v[18:19], v[142:143], v[212:213]
	v_cvt_pk_bf16_f32 v194, v14, v15
	v_cvt_pk_bf16_f32 v195, v16, v17
	global_store_dwordx4 v[26:27], v[192:195], off offset:256 sc0 sc1
	v_lshlrev_b64 v[26:27], 12, v[224:225]
	v_lshl_add_u64 v[18:19], s[42:43], 0, v[26:27]
	v_pk_fma_f32 v[32:33], v[20:21], v[144:145], v[214:215]
	v_pk_fma_f32 v[140:141], v[12:13], v[140:141], v[210:211]
	v_pk_fma_f32 v[138:139], v[10:11], v[138:139], v[208:209]
	v_cvt_pk_bf16_f32 v10, v142, v143
	v_cvt_pk_bf16_f32 v11, v32, v33
	v_lshl_add_u64 v[144:145], v[18:19], 0, v[180:181]
	v_cvt_pk_bf16_f32 v12, v138, v139
	v_cvt_pk_bf16_f32 v13, v140, v141
	global_store_dwordx4 v[144:145], v[10:13], off sc0 sc1
	s_waitcnt vmcnt(3)
	v_pk_fma_f32 v[18:19], v[8:9], v[136:137], v[222:223]
	v_pk_fma_f32 v[20:21], v[6:7], v[134:135], v[220:221]
	v_pk_fma_f32 v[12:13], v[4:5], v[132:133], v[218:219]
	v_pk_fma_f32 v[10:11], v[2:3], v[130:131], v[216:217]
	v_cvt_pk_bf16_f32 v2, v20, v21
	v_cvt_pk_bf16_f32 v3, v18, v19
	s_nop 0
	v_cvt_pk_bf16_f32 v4, v10, v11
	v_cvt_pk_bf16_f32 v5, v12, v13
	global_store_dwordx4 v[144:145], v[2:5], off offset:256 sc0 sc1
	s_nop 1
	v_and_b32_e32 v3, 64, v242
	v_xor_b32_e32 v2, 16, v242
	v_add_u32_e32 v3, 64, v3
	v_cmp_lt_i32_e32 vcc, v2, v3
	v_xor_b32_e32 v5, 32, v242
	s_lshl_b32 s0, s35, 2
	v_cndmask_b32_e32 v2, v242, v2, vcc
	v_lshlrev_b32_e32 v2, 2, v2
	ds_bpermute_b32 v4, v2, v186
	v_cmp_lt_i32_e32 vcc, v5, v3
	s_add_i32 s50, s0, 0
	s_add_i32 s50, s50, 0x21000
	v_cndmask_b32_e32 v3, v242, v5, vcc
	v_lshlrev_b32_e32 v3, 2, v3
	s_waitcnt lgkmcnt(0)
	v_add_f32_e32 v4, v186, v4
	ds_bpermute_b32 v5, v3, v4
	v_cmp_eq_u32_e32 vcc, 0, v190
	s_and_saveexec_b64 s[0:1], vcc
	s_cbranch_execz .LBB9_1232
	s_lshl_b32 s3, s34, 10
	s_add_i32 s3, s50, s3
	v_lshl_add_u32 v6, v184, 4, s3
	s_waitcnt lgkmcnt(0)
	v_add_f32_e32 v4, v4, v5
	ds_write_b32 v6, v4

; __device__ __forceinline__ unsigned cvt_pk_bf16(float lo, float hi) { unsigned r; asm volatile("v_cvt_pk_bf16_f32 %0, %1, %2" : "=v"(r) : "v"(lo), "v"(hi)); return r; }
;     __device__ __forceinline__ void fuse_tail(f32x4 (&acc)[2][2][4][2], const float (&ssq)[2][4], const Unit& u, int wr, int wc, int fr, int fq, int mi, int row0, int col0) const {
;     ...
;         bf16_t* XN = (bf16_t*)((char*)X + RN_DXN);
;         const float* sh = mods_l + nsh_off + (size_t)mi * MODW + col0;
; #pragma unroll
;         for (int bj = 0; bj < 2; ++bj) { f32x4 GG[2], SS[2];
; #pragma unroll
;             for (int n = 0; n < 2; ++n) { GG[n] = *(const f32x4*)(ng + col0 + bj * HALF + 4 * n) * (*(const f32x4*)(sh + D + bj * HALF + 4 * n) + 1.f); SS[n] = *(const f32x4*)(sh + bj * HALF + 4 * n); }
; #pragma unroll
;             for (int ai = 0; ai < 2; ++ai)
; #pragma unroll
;                 for (int m = 0; m < 4; ++m) { const float rstd = S[ai * HALF + wr * 64 + m * 16 + fr];
;                     const f32x4 h0 = acc[ai][bj][m][0] * rstd * GG[0] + SS[0], h1 = acc[ai][bj][m][1] * rstd * GG[1] + SS[1];
;                     u32x4 w; w.x = cvt_pk_bf16(h0[0], h0[1]); w.y = cvt_pk_bf16(h0[2], h0[3]); w.z = cvt_pk_bf16(h1[0], h1[1]); w.w = cvt_pk_bf16(h1[2], h1[3]);
;                     *(u32x4*)(XN + (size_t)(row0 + ai * HALF + m * 16) * D + col0 + bj * HALF) = w; } }
.LBB9_1273:
	s_or_b64 exec, exec, s[46:47]
	s_add_u32 s0, s81, s48
	s_addc_u32 s1, s82, s5
	v_lshl_add_u64 v[130:131], s[0:1], 0, v[178:179]
	s_mov_b64 s[0:1], 0x2000
	v_lshl_add_u64 v[144:145], v[130:131], 0, s[0:1]
	s_and_b32 s0, s4, 0xffffff00
	s_add_i32 s0, s0, 0
	v_add_co_u32_e32 v136, vcc, s28, v130
	s_waitcnt lgkmcnt(0)
	s_barrier
	v_lshl_add_u32 v2, v184, 2, s0
	v_lshl_add_u64 v[132:133], s[14:15], 0, v[178:179]
	v_addc_co_u32_e32 v137, vcc, 0, v131, vcc
	v_add_u32_e32 v184, 0x22000, v2
	global_load_dwordx4 v[190:193], v[132:133], off offset:16
	global_load_dwordx4 v[2:5], v[132:133], off
	global_load_dwordx4 v[6:9], v[136:137], off
	global_load_dwordx4 v[178:181], v[144:145], off offset:16
	v_lshl_add_u64 v[134:135], v[176:177], 1, s[36:37]
	v_lshl_add_u64 v[26:27], v[134:135], 0, v[26:27]
	s_mov_b64 s[0:1], 0x2200
	s_waitcnt vmcnt(1)
	v_pk_add_f32 v[8:9], v[8:9], 1.0 op_sel_hi:[1,0]
	v_pk_add_f32 v[6:7], v[6:7], 1.0 op_sel_hi:[1,0]
	v_pk_mul_f32 v[144:145], v[4:5], v[8:9]
	v_pk_mul_f32 v[176:177], v[2:3], v[6:7]
	global_load_dwordx4 v[2:5], v[130:131], off offset:16
	global_load_dwordx4 v[6:9], v[130:131], off
	ds_read_b32 v186, v184
	s_waitcnt vmcnt(2)
	v_pk_add_f32 v[180:181], v[180:181], 1.0 op_sel_hi:[1,0]
	v_pk_add_f32 v[194:195], v[178:179], 1.0 op_sel_hi:[1,0]
	v_pk_mul_f32 v[178:179], v[192:193], v[180:181]
	v_pk_mul_f32 v[180:181], v[190:191], v[194:195]
	s_waitcnt lgkmcnt(0)
	v_pk_mul_f32 v[160:161], v[160:161], v[186:187] op_sel_hi:[1,0]
	v_pk_mul_f32 v[162:163], v[162:163], v[186:187] op_sel_hi:[1,0]
	v_pk_mul_f32 v[128:129], v[128:129], v[186:187] op_sel_hi:[1,0]
	v_pk_mul_f32 v[126:127], v[126:127], v[186:187] op_sel_hi:[1,0]
	s_waitcnt vmcnt(1)
	v_pk_fma_f32 v[128:129], v[180:181], v[128:129], v[2:3]
	s_waitcnt vmcnt(0)
	v_pk_fma_f32 v[190:191], v[144:145], v[160:161], v[8:9]
	v_pk_fma_f32 v[160:161], v[176:177], v[162:163], v[6:7]
	v_pk_fma_f32 v[126:127], v[178:179], v[126:127], v[4:5]
	v_cvt_pk_bf16_f32 v160, v160, v161
	v_cvt_pk_bf16_f32 v161, v190, v191
	v_cvt_pk_bf16_f32 v162, v128, v129
	s_nop 0
	v_cvt_pk_bf16_f32 v163, v126, v127
	ds_read_b32 v128, v184 offset:64
	v_lshl_add_u64 v[126:127], v[134:135], 0, v[158:159]
	global_store_dwordx4 v[126:127], v[160:163], off sc0 sc1
	s_waitcnt lgkmcnt(0)
	v_pk_mul_f32 v[112:113], v[112:113], v[128:129] op_sel_hi:[1,0]
	v_pk_mul_f32 v[108:109], v[108:109], v[128:129] op_sel_hi:[1,0]
	v_pk_mul_f32 v[124:125], v[124:125], v[128:129] op_sel_hi:[1,0]
	v_pk_fma_f32 v[112:113], v[144:145], v[112:113], v[8:9]
	v_pk_mul_f32 v[110:111], v[110:111], v[128:129] op_sel_hi:[1,0]
	v_pk_fma_f32 v[108:109], v[178:179], v[108:109], v[4:5]
	v_pk_fma_f32 v[124:125], v[176:177], v[124:125], v[6:7]
	v_pk_fma_f32 v[128:129], v[180:181], v[110:111], v[2:3]
	v_cvt_pk_bf16_f32 v110, v124, v125
	v_cvt_pk_bf16_f32 v111, v112, v113
	s_nop 0
	v_cvt_pk_bf16_f32 v112, v128, v129
	v_cvt_pk_bf16_f32 v113, v108, v109
	v_lshl_add_u64 v[108:109], v[134:135], 0, v[122:123]
	global_store_dwordx4 v[108:109], v[110:113], off sc0 sc1
	ds_read_b32 v110, v184 offset:128
	s_waitcnt lgkmcnt(0)
	v_pk_mul_f32 v[94:95], v[94:95], v[110:111] op_sel_hi:[1,0]
	v_pk_mul_f32 v[112:113], v[164:165], v[110:111] op_sel_hi:[1,0]
	v_pk_mul_f32 v[122:123], v[166:167], v[110:111] op_sel_hi:[1,0]
	v_pk_fma_f32 v[112:113], v[144:145], v[112:113], v[8:9]
	v_pk_mul_f32 v[92:93], v[92:93], v[110:111] op_sel_hi:[1,0]
	v_pk_fma_f32 v[94:95], v[180:181], v[94:95], v[2:3]
	v_pk_fma_f32 v[122:123], v[176:177], v[122:123], v[6:7]
	v_pk_fma_f32 v[92:93], v[178:179], v[92:93], v[4:5]
	v_cvt_pk_bf16_f32 v110, v122, v123
	v_cvt_pk_bf16_f32 v111, v112, v113
	v_cvt_pk_bf16_f32 v112, v94, v95
	s_nop 0
	v_cvt_pk_bf16_f32 v113, v92, v93
	ds_read_b32 v94, v184 offset:192
	v_lshl_add_u64 v[92:93], v[134:135], 0, v[106:107]
	global_store_dwordx4 v[92:93], v[110:113], off sc0 sc1
	s_waitcnt lgkmcnt(0)
	v_pk_mul_f32 v[84:85], v[84:85], v[94:95] op_sel_hi:[1,0]
	v_pk_mul_f32 v[76:77], v[76:77], v[94:95] op_sel_hi:[1,0]
	v_pk_mul_f32 v[96:97], v[96:97], v[94:95] op_sel_hi:[1,0]
	v_pk_fma_f32 v[84:85], v[144:145], v[84:85], v[8:9]
	v_pk_mul_f32 v[82:83], v[82:83], v[94:95] op_sel_hi:[1,0]
	v_pk_fma_f32 v[76:77], v[178:179], v[76:77], v[4:5]
	v_pk_fma_f32 v[96:97], v[176:177], v[96:97], v[6:7]
	v_pk_fma_f32 v[94:95], v[180:181], v[82:83], v[2:3]
	v_cvt_pk_bf16_f32 v82, v96, v97
	v_cvt_pk_bf16_f32 v83, v84, v85
	s_nop 0
	v_cvt_pk_bf16_f32 v84, v94, v95
	v_cvt_pk_bf16_f32 v85, v76, v77
	v_lshl_add_u64 v[76:77], v[134:135], 0, v[90:91]
	global_store_dwordx4 v[76:77], v[82:85], off sc0 sc1
	ds_read_b32 v82, v184 offset:512
	s_waitcnt lgkmcnt(0)
	v_pk_mul_f32 v[62:63], v[62:63], v[82:83] op_sel_hi:[1,0]
	v_pk_mul_f32 v[84:85], v[168:169], v[82:83] op_sel_hi:[1,0]
	v_pk_mul_f32 v[90:91], v[170:171], v[82:83] op_sel_hi:[1,0]
	v_pk_fma_f32 v[84:85], v[144:145], v[84:85], v[8:9]
	v_pk_mul_f32 v[60:61], v[60:61], v[82:83] op_sel_hi:[1,0]
	v_pk_fma_f32 v[62:63], v[180:181], v[62:63], v[2:3]
	v_pk_fma_f32 v[90:91], v[176:177], v[90:91], v[6:7]
	v_pk_fma_f32 v[60:61], v[178:179], v[60:61], v[4:5]
	v_cvt_pk_bf16_f32 v82, v90, v91
	v_cvt_pk_bf16_f32 v83, v84, v85
	v_cvt_pk_bf16_f32 v84, v62, v63
	s_nop 0
	v_cvt_pk_bf16_f32 v85, v60, v61
	ds_read_b32 v62, v184 offset:576
	v_lshl_add_u64 v[60:61], v[134:135], 0, v[74:75]
	global_store_dwordx4 v[60:61], v[82:85], off sc0 sc1
	s_waitcnt lgkmcnt(0)
; __device__ __forceinline__ unsigned cvt_pk_bf16(float lo, float hi) { unsigned r; asm volatile("v_cvt_pk_bf16_f32 %0, %1, %2" : "=v"(r) : "v"(lo), "v"(hi)); return r; }
;     __device__ __forceinline__ void fuse_tail(f32x4 (&acc)[2][2][4][2], const float (&ssq)[2][4], const Unit& u, int wr, int wc, int fr, int fq, int mi, int row0, int col0) const {
;     ...
;         bf16_t* XN = (bf16_t*)((char*)X + RN_DXN);
;         const float* sh = mods_l + nsh_off + (size_t)mi * MODW + col0;
; #pragma unroll
;         for (int bj = 0; bj < 2; ++bj) { f32x4 GG[2], SS[2];
; #pragma unroll
;             for (int n = 0; n < 2; ++n) { GG[n] = *(const f32x4*)(ng + col0 + bj * HALF + 4 * n) * (*(const f32x4*)(sh + D + bj * HALF + 4 * n) + 1.f); SS[n] = *(const f32x4*)(sh + bj * HALF + 4 * n); }
; #pragma unroll
;             for (int ai = 0; ai < 2; ++ai)
; #pragma unroll
;                 for (int m = 0; m < 4; ++m) { const float rstd = S[ai * HALF + wr * 64 + m * 16 + fr];
;                     const f32x4 h0 = acc[ai][bj][m][0] * rstd * GG[0] + SS[0], h1 = acc[ai][bj][m][1] * rstd * GG[1] + SS[1];
;                     u32x4 w; w.x = cvt_pk_bf16(h0[0], h0[1]); w.y = cvt_pk_bf16(h0[2], h0[3]); w.z = cvt_pk_bf16(h1[0], h1[1]); w.w = cvt_pk_bf16(h1[2], h1[3]);
;                     *(u32x4*)(XN + (size_t)(row0 + ai * HALF + m * 16) * D + col0 + bj * HALF) = w; } }
	v_pk_mul_f32 v[52:53], v[52:53], v[62:63] op_sel_hi:[1,0]
	v_pk_mul_f32 v[44:45], v[44:45], v[62:63] op_sel_hi:[1,0]
	v_pk_mul_f32 v[64:65], v[64:65], v[62:63] op_sel_hi:[1,0]
	v_pk_fma_f32 v[52:53], v[144:145], v[52:53], v[8:9]
	v_pk_mul_f32 v[50:51], v[50:51], v[62:63] op_sel_hi:[1,0]
	v_pk_fma_f32 v[44:45], v[178:179], v[44:45], v[4:5]
	v_pk_fma_f32 v[64:65], v[176:177], v[64:65], v[6:7]
	v_pk_fma_f32 v[62:63], v[180:181], v[50:51], v[2:3]
	v_cvt_pk_bf16_f32 v50, v64, v65
	v_cvt_pk_bf16_f32 v51, v52, v53
	s_nop 0
	v_cvt_pk_bf16_f32 v52, v62, v63
	v_cvt_pk_bf16_f32 v53, v44, v45
	v_lshl_add_u64 v[44:45], v[134:135], 0, v[58:59]
	global_store_dwordx4 v[44:45], v[50:53], off sc0 sc1
	ds_read_b32 v50, v184 offset:640
	s_waitcnt lgkmcnt(0)
	v_pk_mul_f32 v[30:31], v[30:31], v[50:51] op_sel_hi:[1,0]
	v_pk_mul_f32 v[52:53], v[172:173], v[50:51] op_sel_hi:[1,0]
	v_pk_mul_f32 v[58:59], v[174:175], v[50:51] op_sel_hi:[1,0]
	v_pk_fma_f32 v[52:53], v[144:145], v[52:53], v[8:9]
	v_pk_mul_f32 v[28:29], v[28:29], v[50:51] op_sel_hi:[1,0]
	v_pk_fma_f32 v[30:31], v[180:181], v[30:31], v[2:3]
	v_pk_fma_f32 v[58:59], v[176:177], v[58:59], v[6:7]
	v_pk_fma_f32 v[28:29], v[178:179], v[28:29], v[4:5]
	v_cvt_pk_bf16_f32 v50, v58, v59
	v_cvt_pk_bf16_f32 v51, v52, v53
	v_cvt_pk_bf16_f32 v52, v30, v31
	s_nop 0
	v_cvt_pk_bf16_f32 v53, v28, v29
	ds_read_b32 v30, v184 offset:704
	v_lshl_add_u64 v[28:29], v[134:135], 0, v[42:43]
	global_store_dwordx4 v[28:29], v[50:53], off sc0 sc1
	s_waitcnt lgkmcnt(0)
	v_pk_mul_f32 v[32:33], v[32:33], v[30:31] op_sel_hi:[1,0]
	v_pk_mul_f32 v[42:43], v[142:143], v[30:31] op_sel_hi:[1,0]
	v_pk_fma_f32 v[8:9], v[144:145], v[32:33], v[8:9]
	v_pk_mul_f32 v[32:33], v[140:141], v[30:31] op_sel_hi:[1,0]
	v_pk_mul_f32 v[30:31], v[138:139], v[30:31] op_sel_hi:[1,0]
	v_pk_fma_f32 v[32:33], v[178:179], v[32:33], v[4:5]
	v_pk_fma_f32 v[4:5], v[180:181], v[30:31], v[2:3]
	v_pk_fma_f32 v[6:7], v[176:177], v[42:43], v[6:7]
	v_lshl_add_u64 v[30:31], v[130:131], 0, s[0:1]
	v_cvt_pk_bf16_f32 v2, v6, v7
	v_cvt_pk_bf16_f32 v3, v8, v9
	v_cvt_pk_bf16_f32 v4, v4, v5
	v_cvt_pk_bf16_f32 v5, v32, v33
	global_store_dwordx4 v[26:27], v[2:5], off sc0 sc1
	global_load_dwordx4 v[50:53], v[132:133], off offset:528
	s_nop 0
	global_load_dwordx4 v[2:5], v[132:133], off offset:512
	global_load_dwordx4 v[6:9], v[136:137], off offset:512
	global_load_dwordx4 v[62:65], v[30:31], off offset:16
	s_waitcnt vmcnt(1)
	v_pk_add_f32 v[8:9], v[8:9], 1.0 op_sel_hi:[1,0]
	v_pk_add_f32 v[6:7], v[6:7], 1.0 op_sel_hi:[1,0]
	v_pk_mul_f32 v[30:31], v[4:5], v[8:9]
	v_pk_mul_f32 v[32:33], v[2:3], v[6:7]
	global_load_dwordx4 v[2:5], v[130:131], off offset:528
	global_load_dwordx4 v[6:9], v[130:131], off offset:512
	s_waitcnt vmcnt(2)
	v_pk_add_f32 v[42:43], v[64:65], 1.0 op_sel_hi:[1,0]
	v_pk_add_f32 v[58:59], v[62:63], 1.0 op_sel_hi:[1,0]
	v_pk_mul_f32 v[42:43], v[52:53], v[42:43]
	ds_read_b32 v52, v184
	v_pk_mul_f32 v[50:51], v[50:51], v[58:59]
	s_waitcnt lgkmcnt(0)
	v_pk_mul_f32 v[58:59], v[120:121], v[52:53] op_sel_hi:[1,0]
	v_pk_mul_f32 v[62:63], v[118:119], v[52:53] op_sel_hi:[1,0]
	v_pk_mul_f32 v[64:65], v[116:117], v[52:53] op_sel_hi:[1,0]
	v_pk_mul_f32 v[52:53], v[114:115], v[52:53] op_sel_hi:[1,0]
	s_waitcnt vmcnt(1)
	v_pk_fma_f32 v[74:75], v[42:43], v[64:65], v[4:5]
	s_waitcnt vmcnt(0)
	v_pk_fma_f32 v[62:63], v[32:33], v[62:63], v[6:7]
	v_pk_fma_f32 v[52:53], v[50:51], v[52:53], v[2:3]
	v_pk_fma_f32 v[58:59], v[30:31], v[58:59], v[8:9]
	v_cvt_pk_bf16_f32 v62, v62, v63
	s_nop 0
	v_cvt_pk_bf16_f32 v63, v58, v59
	v_cvt_pk_bf16_f32 v64, v52, v53
	v_cvt_pk_bf16_f32 v65, v74, v75
	ds_read_b32 v52, v184 offset:64
	global_store_dwordx4 v[126:127], v[62:65], off offset:256 sc0 sc1
	s_waitcnt lgkmcnt(0)
	v_pk_mul_f32 v[58:59], v[104:105], v[52:53] op_sel_hi:[1,0]
	v_pk_mul_f32 v[62:63], v[102:103], v[52:53] op_sel_hi:[1,0]
	v_pk_mul_f32 v[64:65], v[100:101], v[52:53] op_sel_hi:[1,0]
	v_pk_mul_f32 v[52:53], v[98:99], v[52:53] op_sel_hi:[1,0]
	v_pk_fma_f32 v[62:63], v[32:33], v[62:63], v[6:7]
	v_pk_fma_f32 v[52:53], v[50:51], v[52:53], v[2:3]
	v_pk_fma_f32 v[58:59], v[30:31], v[58:59], v[8:9]
	v_pk_fma_f32 v[74:75], v[42:43], v[64:65], v[4:5]
	v_cvt_pk_bf16_f32 v62, v62, v63
	v_cvt_pk_bf16_f32 v63, v58, v59
	v_cvt_pk_bf16_f32 v64, v52, v53
	s_nop 0
	v_cvt_pk_bf16_f32 v65, v74, v75
	ds_read_b32 v52, v184 offset:128
	global_store_dwordx4 v[108:109], v[62:65], off offset:256 sc0 sc1
	s_waitcnt lgkmcnt(0)
; __device__ __forceinline__ unsigned cvt_pk_bf16(float lo, float hi) { unsigned r; asm volatile("v_cvt_pk_bf16_f32 %0, %1, %2" : "=v"(r) : "v"(lo), "v"(hi)); return r; }
;     __device__ __forceinline__ void fuse_tail(f32x4 (&acc)[2][2][4][2], const float (&ssq)[2][4], const Unit& u, int wr, int wc, int fr, int fq, int mi, int row0, int col0) const {
;     ...
;         bf16_t* XN = (bf16_t*)((char*)X + RN_DXN);
;         const float* sh = mods_l + nsh_off + (size_t)mi * MODW + col0;
; #pragma unroll
;         for (int bj = 0; bj < 2; ++bj) { f32x4 GG[2], SS[2];
; #pragma unroll
;             for (int n = 0; n < 2; ++n) { GG[n] = *(const f32x4*)(ng + col0 + bj * HALF + 4 * n) * (*(const f32x4*)(sh + D + bj * HALF + 4 * n) + 1.f); SS[n] = *(const f32x4*)(sh + bj * HALF + 4 * n); }
; #pragma unroll
;             for (int ai = 0; ai < 2; ++ai)
; #pragma unroll
;                 for (int m = 0; m < 4; ++m) { const float rstd = S[ai * HALF + wr * 64 + m * 16 + fr];
;                     const f32x4 h0 = acc[ai][bj][m][0] * rstd * GG[0] + SS[0], h1 = acc[ai][bj][m][1] * rstd * GG[1] + SS[1];
;                     u32x4 w; w.x = cvt_pk_bf16(h0[0], h0[1]); w.y = cvt_pk_bf16(h0[2], h0[3]); w.z = cvt_pk_bf16(h1[0], h1[1]); w.w = cvt_pk_bf16(h1[2], h1[3]);
;                     *(u32x4*)(XN + (size_t)(row0 + ai * HALF + m * 16) * D + col0 + bj * HALF) = w; } }
	v_pk_mul_f32 v[58:59], v[88:89], v[52:53] op_sel_hi:[1,0]
	v_pk_mul_f32 v[62:63], v[86:87], v[52:53] op_sel_hi:[1,0]
	v_pk_mul_f32 v[64:65], v[80:81], v[52:53] op_sel_hi:[1,0]
	v_pk_mul_f32 v[52:53], v[78:79], v[52:53] op_sel_hi:[1,0]
	v_pk_fma_f32 v[62:63], v[32:33], v[62:63], v[6:7]
	v_pk_fma_f32 v[52:53], v[50:51], v[52:53], v[2:3]
	v_pk_fma_f32 v[58:59], v[30:31], v[58:59], v[8:9]
	v_pk_fma_f32 v[74:75], v[42:43], v[64:65], v[4:5]
	v_cvt_pk_bf16_f32 v62, v62, v63
	v_cvt_pk_bf16_f32 v63, v58, v59
	v_cvt_pk_bf16_f32 v64, v52, v53
	s_nop 0
	v_cvt_pk_bf16_f32 v65, v74, v75
	ds_read_b32 v52, v184 offset:192
	global_store_dwordx4 v[92:93], v[62:65], off offset:256 sc0 sc1
	s_waitcnt lgkmcnt(0)
	v_pk_mul_f32 v[58:59], v[72:73], v[52:53] op_sel_hi:[1,0]
	v_pk_mul_f32 v[62:63], v[70:71], v[52:53] op_sel_hi:[1,0]
	v_pk_mul_f32 v[64:65], v[68:69], v[52:53] op_sel_hi:[1,0]
	v_pk_mul_f32 v[52:53], v[66:67], v[52:53] op_sel_hi:[1,0]
	v_pk_fma_f32 v[62:63], v[32:33], v[62:63], v[6:7]
	v_pk_fma_f32 v[52:53], v[50:51], v[52:53], v[2:3]
	v_pk_fma_f32 v[58:59], v[30:31], v[58:59], v[8:9]
	v_pk_fma_f32 v[66:67], v[42:43], v[64:65], v[4:5]
	v_cvt_pk_bf16_f32 v62, v62, v63
	v_cvt_pk_bf16_f32 v63, v58, v59
	v_cvt_pk_bf16_f32 v64, v52, v53
	s_nop 0
	v_cvt_pk_bf16_f32 v65, v66, v67
	ds_read_b32 v52, v184 offset:512
	global_store_dwordx4 v[76:77], v[62:65], off offset:256 sc0 sc1
	s_waitcnt lgkmcnt(0)
	v_pk_mul_f32 v[54:55], v[54:55], v[52:53] op_sel_hi:[1,0]
	v_pk_mul_f32 v[48:49], v[48:49], v[52:53] op_sel_hi:[1,0]
	v_pk_mul_f32 v[46:47], v[46:47], v[52:53] op_sel_hi:[1,0]
	v_pk_mul_f32 v[56:57], v[56:57], v[52:53] op_sel_hi:[1,0]
	v_pk_fma_f32 v[54:55], v[32:33], v[54:55], v[6:7]
	v_pk_fma_f32 v[52:53], v[42:43], v[48:49], v[4:5]
	v_pk_fma_f32 v[48:49], v[50:51], v[46:47], v[2:3]
	v_cvt_pk_bf16_f32 v46, v54, v55
	v_pk_fma_f32 v[56:57], v[30:31], v[56:57], v[8:9]
	s_nop 0
	v_cvt_pk_bf16_f32 v47, v56, v57
	v_cvt_pk_bf16_f32 v48, v48, v49
	v_cvt_pk_bf16_f32 v49, v52, v53
	global_store_dwordx4 v[60:61], v[46:49], off offset:256 sc0 sc1
	ds_read_b32 v46, v184 offset:576
	s_waitcnt lgkmcnt(0)
	v_pk_mul_f32 v[38:39], v[38:39], v[46:47] op_sel_hi:[1,0]
	v_pk_mul_f32 v[36:37], v[36:37], v[46:47] op_sel_hi:[1,0]
	v_pk_mul_f32 v[34:35], v[34:35], v[46:47] op_sel_hi:[1,0]
	v_pk_mul_f32 v[40:41], v[40:41], v[46:47] op_sel_hi:[1,0]
	v_pk_fma_f32 v[38:39], v[32:33], v[38:39], v[6:7]
	v_pk_fma_f32 v[46:47], v[42:43], v[36:37], v[4:5]
	v_pk_fma_f32 v[36:37], v[50:51], v[34:35], v[2:3]
	v_cvt_pk_bf16_f32 v34, v38, v39
	v_pk_fma_f32 v[40:41], v[30:31], v[40:41], v[8:9]
	s_nop 0
	v_cvt_pk_bf16_f32 v35, v40, v41
	v_cvt_pk_bf16_f32 v36, v36, v37
	v_cvt_pk_bf16_f32 v37, v46, v47
	global_store_dwordx4 v[44:45], v[34:37], off offset:256 sc0 sc1
	ds_read_b32 v34, v184 offset:640
	s_waitcnt lgkmcnt(0)
	v_pk_mul_f32 v[22:23], v[22:23], v[34:35] op_sel_hi:[1,0]
	v_pk_mul_f32 v[16:17], v[16:17], v[34:35] op_sel_hi:[1,0]
	v_pk_mul_f32 v[14:15], v[14:15], v[34:35] op_sel_hi:[1,0]
	v_pk_mul_f32 v[24:25], v[24:25], v[34:35] op_sel_hi:[1,0]
	v_pk_fma_f32 v[22:23], v[32:33], v[22:23], v[6:7]
	v_pk_fma_f32 v[34:35], v[42:43], v[16:17], v[4:5]
	v_pk_fma_f32 v[16:17], v[50:51], v[14:15], v[2:3]
	v_cvt_pk_bf16_f32 v14, v22, v23
	v_pk_fma_f32 v[24:25], v[30:31], v[24:25], v[8:9]
	s_nop 0
	v_cvt_pk_bf16_f32 v15, v24, v25
	v_cvt_pk_bf16_f32 v16, v16, v17
	v_cvt_pk_bf16_f32 v17, v34, v35
	global_store_dwordx4 v[28:29], v[14:17], off offset:256 sc0 sc1
	ds_read_b32 v14, v184 offset:704
	s_waitcnt lgkmcnt(0)
	v_pk_mul_f32 v[12:13], v[12:13], v[14:15] op_sel_hi:[1,0]
	v_pk_mul_f32 v[10:11], v[10:11], v[14:15] op_sel_hi:[1,0]
	v_pk_mul_f32 v[16:17], v[18:19], v[14:15] op_sel_hi:[1,0]
	v_pk_mul_f32 v[18:19], v[20:21], v[14:15] op_sel_hi:[1,0]
	v_pk_fma_f32 v[12:13], v[42:43], v[12:13], v[4:5]
	v_pk_fma_f32 v[4:5], v[50:51], v[10:11], v[2:3]
	v_pk_fma_f32 v[8:9], v[30:31], v[16:17], v[8:9]
	v_pk_fma_f32 v[6:7], v[32:33], v[18:19], v[6:7]
	s_nop 0
	v_cvt_pk_bf16_f32 v2, v6, v7
	v_cvt_pk_bf16_f32 v3, v8, v9
	v_cvt_pk_bf16_f32 v4, v4, v5
	v_cvt_pk_bf16_f32 v5, v12, v13
	global_store_dwordx4 v[26:27], v[2:5], off offset:256 sc0 sc1
	s_and_b64 vcc, exec, s[38:39]
	s_mov_b64 s[0:1], -1
	s_cbranch_vccnz .LBB9_1214

; __device__ __forceinline__ unsigned cvt_pk_bf16(float lo, float hi) { unsigned r; asm volatile("v_cvt_pk_bf16_f32 %0, %1, %2" : "=v"(r) : "v"(lo), "v"(hi)); return r; }
;     __device__ __forceinline__ void operator()(f32x4 (&acc)[2][2][4][2], const Unit& u, int wr, int wc, int fr, int fq) const {
;         if (u.sw) {
;             bf16_t* base = (bf16_t*)slab + (size_t)(((u.pm - 32) * 8 + u.pn) * 8 + u.ks) * 65536 + (size_t)(wr * 64 + fr) * 256 + wc * 32 + 8 * fq;
; #pragma unroll
;             for (int ai = 0; ai < 2; ++ai)
; #pragma unroll
;                 for (int m = 0; m < 4; ++m)
; #pragma unroll
;                     for (int bj = 0; bj < 2; ++bj) { const f32x4 v0 = acc[ai][bj][m][0], v1 = acc[ai][bj][m][1];
;                         u32x4 w; w.x = cvt_pk_bf16(v0[0], v0[1]); w.y = cvt_pk_bf16(v0[2], v0[3]); w.z = cvt_pk_bf16(v1[0], v1[1]); w.w = cvt_pk_bf16(v1[2], v1[3]);
;                         *(u32x4*)(base + (size_t)(ai * HALF + m * 16) * 256 + bj * HALF) = w; }
;             return;
.LBB9_1550:
	v_mov_b32_e32 v249, v0
	s_nop 0
	v_readfirstlane_b32 s4, v249
	s_ashr_i32 s35, s4, 8
	s_bfe_u32 s45, s4, 0x20006
	v_and_b32_e32 v248, 15, v249
	s_cmp_eq_u32 s33, 0
	v_bfe_u32 v250, v249, 4, 2
	s_cbranch_scc1 .LBB9_1590
	s_lshl_b32 s9, s46, 3
	s_lshl_b32 s3, s44, 6
	s_add_i32 s5, s5, s9
	s_add_i32 s3, s5, s3
	s_add_i32 s40, s3, 0xfffff800
	s_ashr_i32 s41, s40, 31
	s_lshl_b64 s[40:41], s[40:41], 17
	v_lshl_or_b32 v130, s35, 6, v248
	s_add_u32 s40, s77, s40
	v_ashrrev_i32_e32 v131, 31, v130
	s_addc_u32 s41, s78, s41
	v_lshlrev_b64 v[130:131], 9, v[130:131]
	v_lshl_add_u64 v[130:131], s[40:41], 0, v[130:131]
	s_lshl_b32 s48, s45, 6
	v_lshl_add_u64 v[130:131], v[130:131], 0, s[48:49]
	v_lshlrev_b32_e32 v186, 4, v250
	v_lshl_add_u64 v[130:131], v[130:131], 0, v[186:187]
	v_cvt_pk_bf16_f32 v132, v126, v127
	v_cvt_pk_bf16_f32 v133, v128, v129
	v_cvt_pk_bf16_f32 v134, v122, v123
	v_cvt_pk_bf16_f32 v135, v124, v125
	global_store_dwordx4 v[130:131], v[132:135], off sc0 sc1
	v_add_co_u32_e32 v136, vcc, s28, v130
	s_nop 0
	v_cvt_pk_bf16_f32 v132, v118, v119
	v_cvt_pk_bf16_f32 v133, v120, v121
	v_cvt_pk_bf16_f32 v134, v114, v115
	v_cvt_pk_bf16_f32 v135, v116, v117
	global_store_dwordx4 v[130:131], v[132:135], off offset:256 sc0 sc1
	v_addc_co_u32_e32 v137, vcc, 0, v131, vcc
	s_nop 0
	v_cvt_pk_bf16_f32 v132, v110, v111
	v_cvt_pk_bf16_f32 v133, v112, v113
	v_cvt_pk_bf16_f32 v134, v106, v107
	v_cvt_pk_bf16_f32 v135, v108, v109
	s_movk_i32 s3, 0x4000
	global_store_dwordx4 v[136:137], v[132:135], off sc0 sc1
	s_nop 1
	v_cvt_pk_bf16_f32 v132, v102, v103
	v_cvt_pk_bf16_f32 v133, v104, v105
	v_cvt_pk_bf16_f32 v134, v98, v99
	v_cvt_pk_bf16_f32 v135, v100, v101
	global_store_dwordx4 v[136:137], v[132:135], off offset:256 sc0 sc1
	v_add_co_u32_e32 v136, vcc, s3, v130
	s_nop 0
	v_cvt_pk_bf16_f32 v132, v94, v95
	v_cvt_pk_bf16_f32 v133, v96, v97
	v_cvt_pk_bf16_f32 v134, v90, v91
	v_cvt_pk_bf16_f32 v135, v92, v93
	s_nop 0
	v_addc_co_u32_e32 v137, vcc, 0, v131, vcc
	s_movk_i32 s3, 0x6000
	global_store_dwordx4 v[136:137], v[132:135], off sc0 sc1
	s_nop 1
	v_cvt_pk_bf16_f32 v132, v86, v87
	v_cvt_pk_bf16_f32 v133, v88, v89
	v_cvt_pk_bf16_f32 v134, v82, v83
	v_cvt_pk_bf16_f32 v135, v84, v85
	global_store_dwordx4 v[136:137], v[132:135], off offset:256 sc0 sc1
	v_add_co_u32_e32 v136, vcc, s3, v130
	s_nop 0
	v_cvt_pk_bf16_f32 v132, v78, v79
	v_cvt_pk_bf16_f32 v133, v80, v81
	v_cvt_pk_bf16_f32 v134, v74, v75
	v_cvt_pk_bf16_f32 v135, v76, v77
	s_nop 0
	v_addc_co_u32_e32 v137, vcc, 0, v131, vcc
	global_store_dwordx4 v[136:137], v[132:135], off sc0 sc1
	s_mov_b32 s3, 0x12000
	s_nop 0
	v_cvt_pk_bf16_f32 v132, v70, v71
	v_cvt_pk_bf16_f32 v133, v72, v73
	v_cvt_pk_bf16_f32 v134, v66, v67
	v_cvt_pk_bf16_f32 v135, v68, v69
	global_store_dwordx4 v[136:137], v[132:135], off offset:256 sc0 sc1
	v_add_co_u32_e32 v136, vcc, s59, v130
	s_nop 0
	v_cvt_pk_bf16_f32 v132, v62, v63
	v_cvt_pk_bf16_f32 v133, v64, v65
	v_cvt_pk_bf16_f32 v134, v58, v59
	v_cvt_pk_bf16_f32 v135, v60, v61
	s_nop 0
	v_addc_co_u32_e32 v137, vcc, 0, v131, vcc
	global_store_dwordx4 v[136:137], v[132:135], off sc0 sc1
	s_nop 1
	v_cvt_pk_bf16_f32 v132, v54, v55
	v_cvt_pk_bf16_f32 v133, v56, v57
	v_cvt_pk_bf16_f32 v134, v50, v51
	v_cvt_pk_bf16_f32 v135, v52, v53
	global_store_dwordx4 v[136:137], v[132:135], off offset:256 sc0 sc1
	v_add_co_u32_e32 v136, vcc, s3, v130
	s_nop 0
	v_cvt_pk_bf16_f32 v132, v46, v47
	v_cvt_pk_bf16_f32 v133, v48, v49
	v_cvt_pk_bf16_f32 v134, v42, v43
	v_cvt_pk_bf16_f32 v135, v44, v45
	s_nop 0
	v_addc_co_u32_e32 v137, vcc, 0, v131, vcc
	s_mov_b32 s3, 0x14000
	global_store_dwordx4 v[136:137], v[132:135], off sc0 sc1
	s_nop 1
	v_cvt_pk_bf16_f32 v132, v38, v39
	v_cvt_pk_bf16_f32 v133, v40, v41
	v_cvt_pk_bf16_f32 v134, v34, v35
	v_cvt_pk_bf16_f32 v135, v36, v37
	global_store_dwordx4 v[136:137], v[132:135], off offset:256 sc0 sc1
	v_add_co_u32_e32 v136, vcc, s3, v130
	s_nop 0
	v_cvt_pk_bf16_f32 v132, v30, v31
	v_cvt_pk_bf16_f32 v133, v32, v33
	v_cvt_pk_bf16_f32 v134, v26, v27
	v_cvt_pk_bf16_f32 v135, v28, v29
	s_nop 0
	v_addc_co_u32_e32 v137, vcc, 0, v131, vcc
	s_mov_b32 s3, 0x16000
	global_store_dwordx4 v[136:137], v[132:135], off sc0 sc1
	s_nop 1
	v_cvt_pk_bf16_f32 v132, v22, v23
	v_cvt_pk_bf16_f32 v133, v24, v25
	v_cvt_pk_bf16_f32 v134, v18, v19
	v_cvt_pk_bf16_f32 v135, v20, v21
	global_store_dwordx4 v[136:137], v[132:135], off offset:256 sc0 sc1
	v_add_co_u32_e32 v136, vcc, s3, v130
	s_nop 0
	v_cvt_pk_bf16_f32 v132, v14, v15
	v_cvt_pk_bf16_f32 v133, v16, v17
	v_cvt_pk_bf16_f32 v134, v10, v11
	v_cvt_pk_bf16_f32 v135, v12, v13
	s_nop 0
	v_addc_co_u32_e32 v137, vcc, 0, v131, vcc
	global_store_dwordx4 v[136:137], v[132:135], off sc0 sc1
	v_cvt_pk_bf16_f32 v130, v6, v7
	v_cvt_pk_bf16_f32 v131, v8, v9
	s_nop 1
	v_cvt_pk_bf16_f32 v132, v2, v3
	v_cvt_pk_bf16_f32 v133, v4, v5
	global_store_dwordx4 v[136:137], v[130:133], off offset:256 sc0 sc1
	s_cbranch_execnz .LBB9_1591

; __device__ __forceinline__ unsigned cvt_pk_bf16(float lo, float hi) { unsigned r; asm volatile("v_cvt_pk_bf16_f32 %0, %1, %2" : "=v"(r) : "v"(lo), "v"(hi)); return r; }
;     __device__ __forceinline__ void fuse_tail(f32x4 (&acc)[2][2][4][2], const float (&ssq)[2][4], const Unit& u, int wr, int wc, int fr, int fq, int mi, int row0, int col0) const {
;     ...
;             int r0o = row0; asm volatile("" : "+v"(r0o)); bf16_t* xb = X + (size_t)r0o * D + col0;
; #pragma unroll
;             for (int ai = 0; ai < 2; ++ai)
; #pragma unroll
;                 for (int m = 0; m < 4; ++m)
; #pragma unroll
;                     for (int bj = 0; bj < 2; ++bj) { const f32x4 v0 = acc[ai][bj][m][0], v1 = acc[ai][bj][m][1];
;                         u32x4 w; w.x = cvt_pk_bf16(v0[0], v0[1]); w.y = cvt_pk_bf16(v0[2], v0[3]); w.z = cvt_pk_bf16(v1[0], v1[1]); w.w = cvt_pk_bf16(v1[2], v1[3]);
;                         *(u32x4*)(xb + (size_t)(ai * HALF + m * 16) * D + bj * HALF) = w; }
;         }
;         if (wid == 0) { unsigned sp = 0u;
;             while ((unsigned)__builtin_amdgcn_readfirstlane((int)__hip_atomic_load(pc, __ATOMIC_RELAXED, __HIP_MEMORY_SCOPE_AGENT)) < want) { __builtin_amdgcn_s_sleep(1); if (++sp > (1u << 18)) break; }
.LBB9_1573:
	s_or_b64 exec, exec, s[46:47]
	v_cvt_pk_bf16_f32 v114, v232, v233
	v_cvt_pk_bf16_f32 v115, v230, v231
	v_cvt_pk_bf16_f32 v116, v228, v229
	v_cvt_pk_bf16_f32 v117, v226, v227
	s_mov_b32 s3, 0x30000
	v_ashrrev_i32_e32 v237, 31, v236
	v_lshlrev_b64 v[4:5], 12, v[236:237]
	v_lshl_add_u64 v[4:5], s[42:43], 0, v[4:5]
	v_lshl_add_u64 v[4:5], v[234:235], 1, v[4:5]
	global_store_dwordx4 v[4:5], v[114:117], off sc0 sc1
	v_add_co_u32_e32 v8, vcc, s59, v4
	s_nop 0
	v_cvt_pk_bf16_f32 v114, v208, v209
	v_cvt_pk_bf16_f32 v115, v206, v207
	v_cvt_pk_bf16_f32 v116, v204, v205
	v_cvt_pk_bf16_f32 v117, v202, v203
	global_store_dwordx4 v[4:5], v[114:117], off offset:256 sc0 sc1
	v_addc_co_u32_e32 v9, vcc, 0, v5, vcc
	s_nop 0
	v_cvt_pk_bf16_f32 v114, v110, v111
	v_cvt_pk_bf16_f32 v115, v112, v113
	v_cvt_pk_bf16_f32 v116, v106, v107
	v_cvt_pk_bf16_f32 v117, v108, v109
	global_store_dwordx4 v[8:9], v[114:117], off sc0 sc1
	s_cmp_lg_u32 s35, 0
	s_nop 0
	v_cvt_pk_bf16_f32 v114, v102, v103
	v_cvt_pk_bf16_f32 v115, v104, v105
	v_cvt_pk_bf16_f32 v116, v98, v99
	v_cvt_pk_bf16_f32 v117, v100, v101
	global_store_dwordx4 v[8:9], v[114:117], off offset:256 sc0 sc1
	v_add_co_u32_e32 v8, vcc, s56, v4
	s_nop 0
	v_cvt_pk_bf16_f32 v114, v94, v95
	v_cvt_pk_bf16_f32 v115, v96, v97
	v_cvt_pk_bf16_f32 v116, v90, v91
	v_cvt_pk_bf16_f32 v117, v92, v93
	s_nop 0
	v_addc_co_u32_e32 v9, vcc, 0, v5, vcc
	global_store_dwordx4 v[8:9], v[114:117], off sc0 sc1
	s_nop 1
	v_cvt_pk_bf16_f32 v114, v86, v87
	v_cvt_pk_bf16_f32 v115, v88, v89
	v_cvt_pk_bf16_f32 v116, v82, v83
	v_cvt_pk_bf16_f32 v117, v84, v85
	global_store_dwordx4 v[8:9], v[114:117], off offset:256 sc0 sc1
	v_add_co_u32_e32 v8, vcc, s3, v4
	s_nop 0
	v_cvt_pk_bf16_f32 v114, v78, v79
	v_cvt_pk_bf16_f32 v115, v80, v81
	v_cvt_pk_bf16_f32 v116, v74, v75
	v_cvt_pk_bf16_f32 v117, v76, v77
	s_nop 0
	v_addc_co_u32_e32 v9, vcc, 0, v5, vcc
	global_store_dwordx4 v[8:9], v[114:117], off sc0 sc1
	s_mov_b32 s3, 0x90000
	s_nop 0
	v_cvt_pk_bf16_f32 v114, v70, v71
	v_cvt_pk_bf16_f32 v115, v72, v73
	v_cvt_pk_bf16_f32 v116, v66, v67
	v_cvt_pk_bf16_f32 v117, v68, v69
	global_store_dwordx4 v[8:9], v[114:117], off offset:256 sc0 sc1
	v_add_co_u32_e32 v8, vcc, s7, v4
	s_nop 0
	v_cvt_pk_bf16_f32 v114, v62, v63
	v_cvt_pk_bf16_f32 v115, v64, v65
	v_cvt_pk_bf16_f32 v116, v58, v59
	v_cvt_pk_bf16_f32 v117, v60, v61
	s_nop 0
	v_addc_co_u32_e32 v9, vcc, 0, v5, vcc
	global_store_dwordx4 v[8:9], v[114:117], off sc0 sc1
	s_nop 1
	v_cvt_pk_bf16_f32 v114, v54, v55
	v_cvt_pk_bf16_f32 v115, v56, v57
	v_cvt_pk_bf16_f32 v116, v50, v51
	v_cvt_pk_bf16_f32 v117, v52, v53
	global_store_dwordx4 v[8:9], v[114:117], off offset:256 sc0 sc1
	v_add_co_u32_e32 v8, vcc, s3, v4
	s_nop 0
	v_cvt_pk_bf16_f32 v114, v46, v47
	v_cvt_pk_bf16_f32 v115, v48, v49
	v_cvt_pk_bf16_f32 v116, v42, v43
	v_cvt_pk_bf16_f32 v117, v44, v45
	s_nop 0
	v_addc_co_u32_e32 v9, vcc, 0, v5, vcc
	global_store_dwordx4 v[8:9], v[114:117], off sc0 sc1
	s_mov_b32 s3, 0xb0000
	s_nop 0
	v_cvt_pk_bf16_f32 v114, v38, v39
	v_cvt_pk_bf16_f32 v115, v40, v41
	v_cvt_pk_bf16_f32 v116, v34, v35
	v_cvt_pk_bf16_f32 v117, v36, v37
	global_store_dwordx4 v[8:9], v[114:117], off offset:256 sc0 sc1
	v_add_co_u32_e32 v8, vcc, s91, v4
	s_nop 0
	v_cvt_pk_bf16_f32 v114, v30, v31
	v_cvt_pk_bf16_f32 v115, v32, v33
	v_cvt_pk_bf16_f32 v116, v26, v27
	v_cvt_pk_bf16_f32 v117, v28, v29
	s_nop 0
	v_addc_co_u32_e32 v9, vcc, 0, v5, vcc
	global_store_dwordx4 v[8:9], v[114:117], off sc0 sc1
	v_add_co_u32_e32 v4, vcc, s3, v4
	s_nop 0
	v_cvt_pk_bf16_f32 v114, v22, v23
	v_cvt_pk_bf16_f32 v115, v24, v25
	v_cvt_pk_bf16_f32 v116, v18, v19
	v_cvt_pk_bf16_f32 v117, v20, v21
	global_store_dwordx4 v[8:9], v[114:117], off offset:256 sc0 sc1
	v_addc_co_u32_e32 v5, vcc, 0, v5, vcc
	s_nop 0
	v_cvt_pk_bf16_f32 v114, v122, v123
	v_cvt_pk_bf16_f32 v115, v118, v119
	v_cvt_pk_bf16_f32 v116, v124, v125
	v_cvt_pk_bf16_f32 v117, v120, v121
	global_store_dwordx4 v[4:5], v[114:117], off sc0 sc1
	s_nop 1
	v_cvt_pk_bf16_f32 v114, v16, v17
	v_cvt_pk_bf16_f32 v115, v12, v13
	v_cvt_pk_bf16_f32 v116, v14, v15
	v_cvt_pk_bf16_f32 v117, v10, v11
	global_store_dwordx4 v[4:5], v[114:117], off offset:256 sc0 sc1
	s_cbranch_scc1 .LBB9_1593
	s_mov_b32 s33, 0x40001
	s_branch .LBB9_1576

; __device__ __forceinline__ unsigned cvt_pk_bf16(float lo, float hi) { unsigned r; asm volatile("v_cvt_pk_bf16_f32 %0, %1, %2" : "=v"(r) : "v"(lo), "v"(hi)); return r; }
;     __device__ __forceinline__ void fuse_tail(f32x4 (&acc)[2][2][4][2], const float (&ssq)[2][4], const Unit& u, int wr, int wc, int fr, int fq, int mi, int row0, int col0) const {
;     ...
;         bf16_t* XN = (bf16_t*)((char*)X + RN_DXN);
;         const float* sh = mods_l + nsh_off + (size_t)mi * MODW + col0;
; #pragma unroll
;         for (int bj = 0; bj < 2; ++bj) { f32x4 GG[2], SS[2];
; #pragma unroll
;             for (int n = 0; n < 2; ++n) { GG[n] = *(const f32x4*)(ng + col0 + bj * HALF + 4 * n) * (*(const f32x4*)(sh + D + bj * HALF + 4 * n) + 1.f); SS[n] = *(const f32x4*)(sh + bj * HALF + 4 * n); }
; #pragma unroll
;             for (int ai = 0; ai < 2; ++ai)
; #pragma unroll
;                 for (int m = 0; m < 4; ++m) { const float rstd = S[ai * HALF + wr * 64 + m * 16 + fr];
;                     const f32x4 h0 = acc[ai][bj][m][0] * rstd * GG[0] + SS[0], h1 = acc[ai][bj][m][1] * rstd * GG[1] + SS[1];
;                     u32x4 w; w.x = cvt_pk_bf16(h0[0], h0[1]); w.y = cvt_pk_bf16(h0[2], h0[3]); w.z = cvt_pk_bf16(h1[0], h1[1]); w.w = cvt_pk_bf16(h1[2], h1[3]);
;                     *(u32x4*)(XN + (size_t)(row0 + ai * HALF + m * 16) * D + col0 + bj * HALF) = w; } }
.LBB9_1595:
	s_or_b64 exec, exec, s[44:45]
	s_add_u32 s40, s85, s27
	s_addc_u32 s41, s86, s5
	v_lshlrev_b64 v[2:3], 2, v[234:235]
	v_lshl_add_u64 v[114:115], s[40:41], 0, v[2:3]
	s_and_b32 s3, s4, 0xffffff00
	s_add_i32 s3, s3, 0
	v_add_co_u32_e32 v128, vcc, s28, v114
	s_waitcnt lgkmcnt(0)
	s_barrier
	s_mov_b64 s[40:41], 0x2000
	v_lshl_add_u32 v4, v248, 2, s3
	v_lshl_add_u64 v[116:117], s[18:19], 0, v[2:3]
	v_addc_co_u32_e32 v129, vcc, 0, v115, vcc
	v_lshl_add_u64 v[130:131], v[114:115], 0, s[40:41]
	v_add_u32_e32 v140, 0x22000, v4
	global_load_dwordx4 v[142:145], v[116:117], off offset:16
	global_load_dwordx4 v[2:5], v[116:117], off
	global_load_dwordx4 v[6:9], v[128:129], off
	global_load_dwordx4 v[136:139], v[130:131], off offset:16
	v_lshl_add_u64 v[126:127], v[234:235], 1, s[24:25]
	s_mov_b64 s[4:5], 0x2200
	s_waitcnt vmcnt(1)
	v_pk_add_f32 v[8:9], v[8:9], 1.0 op_sel_hi:[1,0]
	v_pk_add_f32 v[6:7], v[6:7], 1.0 op_sel_hi:[1,0]
	v_pk_mul_f32 v[132:133], v[4:5], v[8:9]
	v_pk_mul_f32 v[134:135], v[2:3], v[6:7]
	global_load_dwordx4 v[2:5], v[114:115], off offset:16
	global_load_dwordx4 v[6:9], v[114:115], off
	s_waitcnt vmcnt(2)
	v_pk_add_f32 v[130:131], v[138:139], 1.0 op_sel_hi:[1,0]
	v_pk_add_f32 v[138:139], v[136:137], 1.0 op_sel_hi:[1,0]
	v_pk_mul_f32 v[136:137], v[144:145], v[130:131]
	ds_read_b32 v130, v140
	v_pk_mul_f32 v[138:139], v[142:143], v[138:139]
	s_waitcnt lgkmcnt(0)
	v_pk_mul_f32 v[142:143], v[230:231], v[130:131] op_sel_hi:[1,0]
	v_pk_mul_f32 v[144:145], v[232:233], v[130:131] op_sel_hi:[1,0]
	s_waitcnt vmcnt(0)
	v_pk_fma_f32 v[146:147], v[132:133], v[142:143], v[8:9]
	v_pk_fma_f32 v[142:143], v[134:135], v[144:145], v[6:7]
	v_pk_mul_f32 v[144:145], v[226:227], v[130:131] op_sel_hi:[1,0]
	v_pk_mul_f32 v[130:131], v[228:229], v[130:131] op_sel_hi:[1,0]
	v_pk_fma_f32 v[148:149], v[136:137], v[144:145], v[4:5]
	v_pk_fma_f32 v[130:131], v[138:139], v[130:131], v[2:3]
	v_cvt_pk_bf16_f32 v142, v142, v143
	v_cvt_pk_bf16_f32 v143, v146, v147
	s_nop 0
	v_cvt_pk_bf16_f32 v144, v130, v131
	v_lshl_add_u64 v[130:131], v[126:127], 0, v[224:225]
	v_cvt_pk_bf16_f32 v145, v148, v149
	global_store_dwordx4 v[130:131], v[142:145], off sc0 sc1
	ds_read_b32 v142, v140 offset:64
	s_waitcnt lgkmcnt(0)
	v_pk_mul_f32 v[110:111], v[110:111], v[142:143] op_sel_hi:[1,0]
	v_pk_mul_f32 v[106:107], v[106:107], v[142:143] op_sel_hi:[1,0]
	v_pk_mul_f32 v[112:113], v[112:113], v[142:143] op_sel_hi:[1,0]
	v_pk_fma_f32 v[110:111], v[134:135], v[110:111], v[6:7]
	v_pk_mul_f32 v[108:109], v[108:109], v[142:143] op_sel_hi:[1,0]
	v_pk_fma_f32 v[106:107], v[138:139], v[106:107], v[2:3]
	v_pk_fma_f32 v[112:113], v[132:133], v[112:113], v[8:9]
	v_pk_fma_f32 v[142:143], v[136:137], v[108:109], v[4:5]
	v_cvt_pk_bf16_f32 v108, v110, v111
	v_cvt_pk_bf16_f32 v109, v112, v113
	v_cvt_pk_bf16_f32 v110, v106, v107
	v_lshl_add_u64 v[106:107], v[126:127], 0, v[222:223]
	v_cvt_pk_bf16_f32 v111, v142, v143
	global_store_dwordx4 v[106:107], v[108:111], off sc0 sc1
	ds_read_b32 v108, v140 offset:128
	s_waitcnt lgkmcnt(0)
	v_pk_mul_f32 v[94:95], v[94:95], v[108:109] op_sel_hi:[1,0]
	v_pk_mul_f32 v[90:91], v[90:91], v[108:109] op_sel_hi:[1,0]
	v_pk_mul_f32 v[96:97], v[96:97], v[108:109] op_sel_hi:[1,0]
	v_pk_fma_f32 v[94:95], v[134:135], v[94:95], v[6:7]
	v_pk_mul_f32 v[92:93], v[92:93], v[108:109] op_sel_hi:[1,0]
	v_pk_fma_f32 v[90:91], v[138:139], v[90:91], v[2:3]
	v_pk_fma_f32 v[96:97], v[132:133], v[96:97], v[8:9]
	v_pk_fma_f32 v[108:109], v[136:137], v[92:93], v[4:5]
	v_cvt_pk_bf16_f32 v92, v94, v95
	v_cvt_pk_bf16_f32 v93, v96, v97
	v_cvt_pk_bf16_f32 v94, v90, v91
	v_lshl_add_u64 v[90:91], v[126:127], 0, v[220:221]
	v_cvt_pk_bf16_f32 v95, v108, v109
	global_store_dwordx4 v[90:91], v[92:95], off sc0 sc1
	ds_read_b32 v92, v140 offset:192
	s_waitcnt lgkmcnt(0)
	v_pk_mul_f32 v[78:79], v[78:79], v[92:93] op_sel_hi:[1,0]
	v_pk_mul_f32 v[74:75], v[74:75], v[92:93] op_sel_hi:[1,0]
	v_pk_mul_f32 v[80:81], v[80:81], v[92:93] op_sel_hi:[1,0]
	v_pk_fma_f32 v[78:79], v[134:135], v[78:79], v[6:7]
	v_pk_mul_f32 v[76:77], v[76:77], v[92:93] op_sel_hi:[1,0]
	v_pk_fma_f32 v[74:75], v[138:139], v[74:75], v[2:3]
	v_pk_fma_f32 v[80:81], v[132:133], v[80:81], v[8:9]
	v_pk_fma_f32 v[92:93], v[136:137], v[76:77], v[4:5]
	v_cvt_pk_bf16_f32 v76, v78, v79
	v_cvt_pk_bf16_f32 v77, v80, v81
	v_cvt_pk_bf16_f32 v78, v74, v75
	v_lshl_add_u64 v[74:75], v[126:127], 0, v[216:217]
	v_cvt_pk_bf16_f32 v79, v92, v93
	global_store_dwordx4 v[74:75], v[76:79], off sc0 sc1
	ds_read_b32 v76, v140 offset:512
	s_waitcnt lgkmcnt(0)
	v_pk_mul_f32 v[62:63], v[62:63], v[76:77] op_sel_hi:[1,0]
	v_pk_mul_f32 v[58:59], v[58:59], v[76:77] op_sel_hi:[1,0]
	v_pk_mul_f32 v[64:65], v[64:65], v[76:77] op_sel_hi:[1,0]
	v_pk_fma_f32 v[62:63], v[134:135], v[62:63], v[6:7]
	v_pk_mul_f32 v[60:61], v[60:61], v[76:77] op_sel_hi:[1,0]
	v_pk_fma_f32 v[58:59], v[138:139], v[58:59], v[2:3]
	v_pk_fma_f32 v[64:65], v[132:133], v[64:65], v[8:9]
	v_pk_fma_f32 v[76:77], v[136:137], v[60:61], v[4:5]
	v_cvt_pk_bf16_f32 v60, v62, v63
	v_cvt_pk_bf16_f32 v61, v64, v65
	v_cvt_pk_bf16_f32 v62, v58, v59
	v_lshl_add_u64 v[58:59], v[126:127], 0, v[218:219]
	v_cvt_pk_bf16_f32 v63, v76, v77
	global_store_dwordx4 v[58:59], v[60:63], off sc0 sc1
	ds_read_b32 v60, v140 offset:576
	s_waitcnt lgkmcnt(0)
; __device__ __forceinline__ unsigned cvt_pk_bf16(float lo, float hi) { unsigned r; asm volatile("v_cvt_pk_bf16_f32 %0, %1, %2" : "=v"(r) : "v"(lo), "v"(hi)); return r; }
;     __device__ __forceinline__ void fuse_tail(f32x4 (&acc)[2][2][4][2], const float (&ssq)[2][4], const Unit& u, int wr, int wc, int fr, int fq, int mi, int row0, int col0) const {
;     ...
;         bf16_t* XN = (bf16_t*)((char*)X + RN_DXN);
;         const float* sh = mods_l + nsh_off + (size_t)mi * MODW + col0;
; #pragma unroll
;         for (int bj = 0; bj < 2; ++bj) { f32x4 GG[2], SS[2];
; #pragma unroll
;             for (int n = 0; n < 2; ++n) { GG[n] = *(const f32x4*)(ng + col0 + bj * HALF + 4 * n) * (*(const f32x4*)(sh + D + bj * HALF + 4 * n) + 1.f); SS[n] = *(const f32x4*)(sh + bj * HALF + 4 * n); }
; #pragma unroll
;             for (int ai = 0; ai < 2; ++ai)
; #pragma unroll
;                 for (int m = 0; m < 4; ++m) { const float rstd = S[ai * HALF + wr * 64 + m * 16 + fr];
;                     const f32x4 h0 = acc[ai][bj][m][0] * rstd * GG[0] + SS[0], h1 = acc[ai][bj][m][1] * rstd * GG[1] + SS[1];
;                     u32x4 w; w.x = cvt_pk_bf16(h0[0], h0[1]); w.y = cvt_pk_bf16(h0[2], h0[3]); w.z = cvt_pk_bf16(h1[0], h1[1]); w.w = cvt_pk_bf16(h1[2], h1[3]);
;                     *(u32x4*)(XN + (size_t)(row0 + ai * HALF + m * 16) * D + col0 + bj * HALF) = w; } }
	v_pk_mul_f32 v[46:47], v[46:47], v[60:61] op_sel_hi:[1,0]
	v_pk_mul_f32 v[42:43], v[42:43], v[60:61] op_sel_hi:[1,0]
	v_pk_mul_f32 v[48:49], v[48:49], v[60:61] op_sel_hi:[1,0]
	v_pk_fma_f32 v[46:47], v[134:135], v[46:47], v[6:7]
	v_pk_mul_f32 v[44:45], v[44:45], v[60:61] op_sel_hi:[1,0]
	v_pk_fma_f32 v[42:43], v[138:139], v[42:43], v[2:3]
	v_pk_fma_f32 v[48:49], v[132:133], v[48:49], v[8:9]
	v_pk_fma_f32 v[60:61], v[136:137], v[44:45], v[4:5]
	v_cvt_pk_bf16_f32 v44, v46, v47
	v_cvt_pk_bf16_f32 v45, v48, v49
	v_cvt_pk_bf16_f32 v46, v42, v43
	v_lshl_add_u64 v[42:43], v[126:127], 0, v[214:215]
	v_cvt_pk_bf16_f32 v47, v60, v61
	global_store_dwordx4 v[42:43], v[44:47], off sc0 sc1
	ds_read_b32 v44, v140 offset:640
	s_waitcnt lgkmcnt(0)
	v_pk_mul_f32 v[30:31], v[30:31], v[44:45] op_sel_hi:[1,0]
	v_pk_mul_f32 v[26:27], v[26:27], v[44:45] op_sel_hi:[1,0]
	v_pk_mul_f32 v[32:33], v[32:33], v[44:45] op_sel_hi:[1,0]
	v_pk_fma_f32 v[30:31], v[134:135], v[30:31], v[6:7]
	v_pk_mul_f32 v[28:29], v[28:29], v[44:45] op_sel_hi:[1,0]
	v_pk_fma_f32 v[26:27], v[138:139], v[26:27], v[2:3]
	v_pk_fma_f32 v[32:33], v[132:133], v[32:33], v[8:9]
	v_pk_fma_f32 v[44:45], v[136:137], v[28:29], v[4:5]
	v_cvt_pk_bf16_f32 v28, v30, v31
	v_cvt_pk_bf16_f32 v29, v32, v33
	v_cvt_pk_bf16_f32 v30, v26, v27
	v_lshl_add_u64 v[26:27], v[126:127], 0, v[212:213]
	v_cvt_pk_bf16_f32 v31, v44, v45
	global_store_dwordx4 v[26:27], v[28:31], off sc0 sc1
	ds_read_b32 v28, v140 offset:704
	s_waitcnt lgkmcnt(0)
	v_pk_mul_f32 v[32:33], v[122:123], v[28:29] op_sel_hi:[1,0]
	v_pk_mul_f32 v[30:31], v[118:119], v[28:29] op_sel_hi:[1,0]
	v_pk_fma_f32 v[6:7], v[134:135], v[32:33], v[6:7]
	v_pk_fma_f32 v[8:9], v[132:133], v[30:31], v[8:9]
	v_pk_mul_f32 v[30:31], v[120:121], v[28:29] op_sel_hi:[1,0]
	v_pk_mul_f32 v[28:29], v[124:125], v[28:29] op_sel_hi:[1,0]
	v_pk_fma_f32 v[30:31], v[136:137], v[30:31], v[4:5]
	v_pk_fma_f32 v[4:5], v[138:139], v[28:29], v[2:3]
	v_lshl_add_u64 v[28:29], v[126:127], 0, v[210:211]
	v_cvt_pk_bf16_f32 v2, v6, v7
	v_cvt_pk_bf16_f32 v3, v8, v9
	v_cvt_pk_bf16_f32 v4, v4, v5
	v_cvt_pk_bf16_f32 v5, v30, v31
	global_store_dwordx4 v[28:29], v[2:5], off sc0 sc1
	v_lshl_add_u64 v[30:31], v[114:115], 0, s[4:5]
	global_load_dwordx4 v[46:49], v[116:117], off offset:528
	global_load_dwordx4 v[2:5], v[116:117], off offset:512
	global_load_dwordx4 v[6:9], v[128:129], off offset:512
	global_load_dwordx4 v[60:63], v[30:31], off offset:16
	s_waitcnt vmcnt(1)
	v_pk_add_f32 v[8:9], v[8:9], 1.0 op_sel_hi:[1,0]
	v_pk_add_f32 v[6:7], v[6:7], 1.0 op_sel_hi:[1,0]
	v_pk_mul_f32 v[30:31], v[4:5], v[8:9]
	v_pk_mul_f32 v[32:33], v[2:3], v[6:7]
	global_load_dwordx4 v[2:5], v[114:115], off offset:528
	global_load_dwordx4 v[6:9], v[114:115], off offset:512
	s_waitcnt vmcnt(2)
	v_pk_add_f32 v[44:45], v[62:63], 1.0 op_sel_hi:[1,0]
	v_pk_add_f32 v[60:61], v[60:61], 1.0 op_sel_hi:[1,0]
	v_pk_mul_f32 v[44:45], v[48:49], v[44:45]
	ds_read_b32 v48, v140
	v_pk_mul_f32 v[46:47], v[46:47], v[60:61]
	s_waitcnt lgkmcnt(0)
	v_pk_mul_f32 v[60:61], v[206:207], v[48:49] op_sel_hi:[1,0]
	v_pk_mul_f32 v[62:63], v[208:209], v[48:49] op_sel_hi:[1,0]
	s_waitcnt vmcnt(0)
	v_pk_fma_f32 v[64:65], v[30:31], v[60:61], v[8:9]
	v_pk_fma_f32 v[60:61], v[32:33], v[62:63], v[6:7]
	v_pk_mul_f32 v[62:63], v[202:203], v[48:49] op_sel_hi:[1,0]
	v_pk_mul_f32 v[48:49], v[204:205], v[48:49] op_sel_hi:[1,0]
	v_pk_fma_f32 v[76:77], v[44:45], v[62:63], v[4:5]
	v_pk_fma_f32 v[48:49], v[46:47], v[48:49], v[2:3]
	v_cvt_pk_bf16_f32 v60, v60, v61
	v_cvt_pk_bf16_f32 v61, v64, v65
	s_nop 0
	v_cvt_pk_bf16_f32 v62, v48, v49
	v_cvt_pk_bf16_f32 v63, v76, v77
	ds_read_b32 v48, v140 offset:64
	global_store_dwordx4 v[130:131], v[60:63], off offset:256 sc0 sc1
	s_waitcnt lgkmcnt(0)
	s_nop 0
	v_pk_mul_f32 v[60:61], v[104:105], v[48:49] op_sel_hi:[1,0]
	v_pk_mul_f32 v[62:63], v[102:103], v[48:49] op_sel_hi:[1,0]
	v_pk_fma_f32 v[64:65], v[30:31], v[60:61], v[8:9]
	v_pk_fma_f32 v[60:61], v[32:33], v[62:63], v[6:7]
	v_pk_mul_f32 v[62:63], v[100:101], v[48:49] op_sel_hi:[1,0]
	v_pk_mul_f32 v[48:49], v[98:99], v[48:49] op_sel_hi:[1,0]
	v_pk_fma_f32 v[76:77], v[44:45], v[62:63], v[4:5]
	v_pk_fma_f32 v[48:49], v[46:47], v[48:49], v[2:3]
	v_cvt_pk_bf16_f32 v60, v60, v61
	v_cvt_pk_bf16_f32 v61, v64, v65
	s_nop 0
	v_cvt_pk_bf16_f32 v62, v48, v49
	v_cvt_pk_bf16_f32 v63, v76, v77
	ds_read_b32 v48, v140 offset:128
	global_store_dwordx4 v[106:107], v[60:63], off offset:256 sc0 sc1
	s_waitcnt lgkmcnt(0)
; __device__ __forceinline__ unsigned cvt_pk_bf16(float lo, float hi) { unsigned r; asm volatile("v_cvt_pk_bf16_f32 %0, %1, %2" : "=v"(r) : "v"(lo), "v"(hi)); return r; }
;     __device__ __forceinline__ void fuse_tail(f32x4 (&acc)[2][2][4][2], const float (&ssq)[2][4], const Unit& u, int wr, int wc, int fr, int fq, int mi, int row0, int col0) const {
;     ...
;         bf16_t* XN = (bf16_t*)((char*)X + RN_DXN);
;         const float* sh = mods_l + nsh_off + (size_t)mi * MODW + col0;
; #pragma unroll
;         for (int bj = 0; bj < 2; ++bj) { f32x4 GG[2], SS[2];
; #pragma unroll
;             for (int n = 0; n < 2; ++n) { GG[n] = *(const f32x4*)(ng + col0 + bj * HALF + 4 * n) * (*(const f32x4*)(sh + D + bj * HALF + 4 * n) + 1.f); SS[n] = *(const f32x4*)(sh + bj * HALF + 4 * n); }
; #pragma unroll
;             for (int ai = 0; ai < 2; ++ai)
; #pragma unroll
;                 for (int m = 0; m < 4; ++m) { const float rstd = S[ai * HALF + wr * 64 + m * 16 + fr];
;                     const f32x4 h0 = acc[ai][bj][m][0] * rstd * GG[0] + SS[0], h1 = acc[ai][bj][m][1] * rstd * GG[1] + SS[1];
;                     u32x4 w; w.x = cvt_pk_bf16(h0[0], h0[1]); w.y = cvt_pk_bf16(h0[2], h0[3]); w.z = cvt_pk_bf16(h1[0], h1[1]); w.w = cvt_pk_bf16(h1[2], h1[3]);
;                     *(u32x4*)(XN + (size_t)(row0 + ai * HALF + m * 16) * D + col0 + bj * HALF) = w; } }
	s_nop 0
	v_pk_mul_f32 v[60:61], v[88:89], v[48:49] op_sel_hi:[1,0]
	v_pk_mul_f32 v[62:63], v[86:87], v[48:49] op_sel_hi:[1,0]
	v_pk_fma_f32 v[64:65], v[30:31], v[60:61], v[8:9]
	v_pk_fma_f32 v[60:61], v[32:33], v[62:63], v[6:7]
	v_pk_mul_f32 v[62:63], v[84:85], v[48:49] op_sel_hi:[1,0]
	v_pk_mul_f32 v[48:49], v[82:83], v[48:49] op_sel_hi:[1,0]
	v_pk_fma_f32 v[76:77], v[44:45], v[62:63], v[4:5]
	v_pk_fma_f32 v[48:49], v[46:47], v[48:49], v[2:3]
	v_cvt_pk_bf16_f32 v60, v60, v61
	v_cvt_pk_bf16_f32 v61, v64, v65
	s_nop 0
	v_cvt_pk_bf16_f32 v62, v48, v49
	v_cvt_pk_bf16_f32 v63, v76, v77
	ds_read_b32 v48, v140 offset:192
	global_store_dwordx4 v[90:91], v[60:63], off offset:256 sc0 sc1
	s_waitcnt lgkmcnt(0)
	s_nop 0
	v_pk_mul_f32 v[60:61], v[72:73], v[48:49] op_sel_hi:[1,0]
	v_pk_mul_f32 v[62:63], v[70:71], v[48:49] op_sel_hi:[1,0]
	v_pk_fma_f32 v[64:65], v[30:31], v[60:61], v[8:9]
	v_pk_fma_f32 v[60:61], v[32:33], v[62:63], v[6:7]
	v_pk_mul_f32 v[62:63], v[68:69], v[48:49] op_sel_hi:[1,0]
	v_pk_mul_f32 v[48:49], v[66:67], v[48:49] op_sel_hi:[1,0]
	v_pk_fma_f32 v[66:67], v[44:45], v[62:63], v[4:5]
	v_pk_fma_f32 v[48:49], v[46:47], v[48:49], v[2:3]
	v_cvt_pk_bf16_f32 v60, v60, v61
	v_cvt_pk_bf16_f32 v61, v64, v65
	s_nop 0
	v_cvt_pk_bf16_f32 v62, v48, v49
	v_cvt_pk_bf16_f32 v63, v66, v67
	ds_read_b32 v48, v140 offset:512
	global_store_dwordx4 v[74:75], v[60:63], off offset:256 sc0 sc1
	s_waitcnt lgkmcnt(0)
	v_pk_mul_f32 v[56:57], v[56:57], v[48:49] op_sel_hi:[1,0]
	v_pk_mul_f32 v[54:55], v[54:55], v[48:49] op_sel_hi:[1,0]
	v_pk_mul_f32 v[52:53], v[52:53], v[48:49] op_sel_hi:[1,0]
	v_pk_mul_f32 v[48:49], v[50:51], v[48:49] op_sel_hi:[1,0]
	v_pk_fma_f32 v[54:55], v[32:33], v[54:55], v[6:7]
	v_pk_fma_f32 v[50:51], v[46:47], v[48:49], v[2:3]
	v_cvt_pk_bf16_f32 v48, v54, v55
	v_pk_fma_f32 v[56:57], v[30:31], v[56:57], v[8:9]
	v_pk_fma_f32 v[52:53], v[44:45], v[52:53], v[4:5]
	v_cvt_pk_bf16_f32 v49, v56, v57
	v_cvt_pk_bf16_f32 v50, v50, v51
	s_nop 0
	v_cvt_pk_bf16_f32 v51, v52, v53
	global_store_dwordx4 v[58:59], v[48:51], off offset:256 sc0 sc1
	ds_read_b32 v48, v140 offset:576
	s_waitcnt lgkmcnt(0)
	v_pk_mul_f32 v[38:39], v[38:39], v[48:49] op_sel_hi:[1,0]
	v_pk_mul_f32 v[36:37], v[36:37], v[48:49] op_sel_hi:[1,0]
	v_pk_mul_f32 v[34:35], v[34:35], v[48:49] op_sel_hi:[1,0]
	v_pk_mul_f32 v[40:41], v[40:41], v[48:49] op_sel_hi:[1,0]
	v_pk_fma_f32 v[38:39], v[32:33], v[38:39], v[6:7]
	v_pk_fma_f32 v[48:49], v[44:45], v[36:37], v[4:5]
	v_pk_fma_f32 v[36:37], v[46:47], v[34:35], v[2:3]
	v_cvt_pk_bf16_f32 v34, v38, v39
	v_pk_fma_f32 v[40:41], v[30:31], v[40:41], v[8:9]
	s_nop 0
	v_cvt_pk_bf16_f32 v35, v40, v41
	v_cvt_pk_bf16_f32 v36, v36, v37
	v_cvt_pk_bf16_f32 v37, v48, v49
	global_store_dwordx4 v[42:43], v[34:37], off offset:256 sc0 sc1
	ds_read_b32 v34, v140 offset:640
	s_waitcnt lgkmcnt(0)
	v_pk_mul_f32 v[22:23], v[22:23], v[34:35] op_sel_hi:[1,0]
	v_pk_mul_f32 v[20:21], v[20:21], v[34:35] op_sel_hi:[1,0]
	v_pk_mul_f32 v[18:19], v[18:19], v[34:35] op_sel_hi:[1,0]
	v_pk_mul_f32 v[24:25], v[24:25], v[34:35] op_sel_hi:[1,0]
	v_pk_fma_f32 v[22:23], v[32:33], v[22:23], v[6:7]
	v_pk_fma_f32 v[34:35], v[44:45], v[20:21], v[4:5]
	v_pk_fma_f32 v[20:21], v[46:47], v[18:19], v[2:3]
	v_cvt_pk_bf16_f32 v18, v22, v23
	v_pk_fma_f32 v[24:25], v[30:31], v[24:25], v[8:9]
	s_nop 0
	v_cvt_pk_bf16_f32 v19, v24, v25
	v_cvt_pk_bf16_f32 v20, v20, v21
	v_cvt_pk_bf16_f32 v21, v34, v35
	global_store_dwordx4 v[26:27], v[18:21], off offset:256 sc0 sc1
	ds_read_b32 v18, v140 offset:704
	s_waitcnt lgkmcnt(0)
	v_pk_mul_f32 v[12:13], v[12:13], v[18:19] op_sel_hi:[1,0]
	s_nop 0
	v_pk_fma_f32 v[8:9], v[30:31], v[12:13], v[8:9]
	v_pk_mul_f32 v[10:11], v[10:11], v[18:19] op_sel_hi:[1,0]
	v_pk_mul_f32 v[12:13], v[14:15], v[18:19] op_sel_hi:[1,0]
	v_pk_mul_f32 v[16:17], v[16:17], v[18:19] op_sel_hi:[1,0]
	v_pk_fma_f32 v[10:11], v[44:45], v[10:11], v[4:5]
	v_pk_fma_f32 v[4:5], v[46:47], v[12:13], v[2:3]
	v_pk_fma_f32 v[6:7], v[32:33], v[16:17], v[6:7]
	s_nop 0
	v_cvt_pk_bf16_f32 v2, v6, v7
	v_cvt_pk_bf16_f32 v3, v8, v9
	v_cvt_pk_bf16_f32 v4, v4, v5
	v_cvt_pk_bf16_f32 v5, v10, v11
	global_store_dwordx4 v[28:29], v[2:5], off offset:256 sc0 sc1
	s_and_b64 vcc, exec, s[38:39]
	s_mov_b64 s[38:39], -1
	s_cbranch_vccnz .LBB9_1530

; __device__ __forceinline__ unsigned cvt_pk_bf16(float lo, float hi) { unsigned r; asm volatile("v_cvt_pk_bf16_f32 %0, %1, %2" : "=v"(r) : "v"(lo), "v"(hi)); return r; }
;     __device__ __forceinline__ void operator()(f32x4 (&acc)[2][2][4][2], const Unit& u, int wr, int wc, int fr, int fq) const {
;         if (u.sw) {
;             bf16_t* base = (bf16_t*)slab + (size_t)(((u.pm - 32) * 8 + u.pn) * 8 + u.ks) * 65536 + (size_t)(wr * 64 + fr) * 256 + wc * 32 + 8 * fq;
; #pragma unroll
;             for (int ai = 0; ai < 2; ++ai)
; #pragma unroll
;                 for (int m = 0; m < 4; ++m)
; #pragma unroll
;                     for (int bj = 0; bj < 2; ++bj) { const f32x4 v0 = acc[ai][bj][m][0], v1 = acc[ai][bj][m][1];
;                         u32x4 w; w.x = cvt_pk_bf16(v0[0], v0[1]); w.y = cvt_pk_bf16(v0[2], v0[3]); w.z = cvt_pk_bf16(v1[0], v1[1]); w.w = cvt_pk_bf16(v1[2], v1[3]);
;                         *(u32x4*)(base + (size_t)(ai * HALF + m * 16) * 256 + bj * HALF) = w; }
;             return;
.LBB9_1621:
	v_mov_b32_e32 v225, v0
	s_nop 0
	v_readfirstlane_b32 s4, v225
	s_ashr_i32 s27, s4, 8
	s_bfe_u32 s35, s4, 0x20006
	v_and_b32_e32 v224, 15, v225
	s_cmp_eq_u32 s5, 0
	v_bfe_u32 v226, v225, 4, 2
	s_cbranch_scc1 .LBB9_1661
	s_lshl_b32 s0, s44, 6
	s_lshl_b32 s1, s46, 3
	s_add_i32 s0, s1, s0
	s_addk_i32 s0, 0xf800
	s_ashr_i32 s1, s0, 31
	s_lshl_b64 s[0:1], s[0:1], 17
	v_lshl_or_b32 v130, s27, 6, v224
	s_add_u32 s0, s10, s0
	v_ashrrev_i32_e32 v131, 31, v130
	s_addc_u32 s1, s11, s1
	v_lshlrev_b64 v[130:131], 9, v[130:131]
	v_lshl_add_u64 v[130:131], s[0:1], 0, v[130:131]
	s_lshl_b32 s48, s35, 6
	v_lshl_add_u64 v[130:131], v[130:131], 0, s[48:49]
	v_lshlrev_b32_e32 v186, 4, v226
	v_lshl_add_u64 v[130:131], v[130:131], 0, v[186:187]
	v_cvt_pk_bf16_f32 v132, v126, v127
	v_cvt_pk_bf16_f32 v133, v128, v129
	v_cvt_pk_bf16_f32 v134, v122, v123
	v_cvt_pk_bf16_f32 v135, v124, v125
	global_store_dwordx4 v[130:131], v[132:135], off sc0 sc1
	v_add_co_u32_e32 v136, vcc, s28, v130
	s_nop 0
	v_cvt_pk_bf16_f32 v132, v118, v119
	v_cvt_pk_bf16_f32 v133, v120, v121
	v_cvt_pk_bf16_f32 v134, v114, v115
	v_cvt_pk_bf16_f32 v135, v116, v117
	global_store_dwordx4 v[130:131], v[132:135], off offset:256 sc0 sc1
	v_addc_co_u32_e32 v137, vcc, 0, v131, vcc
	s_nop 0
	v_cvt_pk_bf16_f32 v132, v110, v111
	v_cvt_pk_bf16_f32 v133, v112, v113
	v_cvt_pk_bf16_f32 v134, v106, v107
	v_cvt_pk_bf16_f32 v135, v108, v109
	s_movk_i32 s0, 0x4000
	global_store_dwordx4 v[136:137], v[132:135], off sc0 sc1
	s_nop 1
	v_cvt_pk_bf16_f32 v132, v102, v103
	v_cvt_pk_bf16_f32 v133, v104, v105
	v_cvt_pk_bf16_f32 v134, v98, v99
	v_cvt_pk_bf16_f32 v135, v100, v101
	global_store_dwordx4 v[136:137], v[132:135], off offset:256 sc0 sc1
	v_add_co_u32_e32 v136, vcc, s0, v130
	s_nop 0
	v_cvt_pk_bf16_f32 v132, v94, v95
	v_cvt_pk_bf16_f32 v133, v96, v97
	v_cvt_pk_bf16_f32 v134, v90, v91
	v_cvt_pk_bf16_f32 v135, v92, v93
	s_nop 0
	v_addc_co_u32_e32 v137, vcc, 0, v131, vcc
	s_movk_i32 s0, 0x6000
	global_store_dwordx4 v[136:137], v[132:135], off sc0 sc1
	s_nop 1
	v_cvt_pk_bf16_f32 v132, v86, v87
	v_cvt_pk_bf16_f32 v133, v88, v89
	v_cvt_pk_bf16_f32 v134, v82, v83
	v_cvt_pk_bf16_f32 v135, v84, v85
	global_store_dwordx4 v[136:137], v[132:135], off offset:256 sc0 sc1
	v_add_co_u32_e32 v136, vcc, s0, v130
	s_nop 0
	v_cvt_pk_bf16_f32 v132, v78, v79
	v_cvt_pk_bf16_f32 v133, v80, v81
	v_cvt_pk_bf16_f32 v134, v74, v75
	v_cvt_pk_bf16_f32 v135, v76, v77
	s_nop 0
	v_addc_co_u32_e32 v137, vcc, 0, v131, vcc
	global_store_dwordx4 v[136:137], v[132:135], off sc0 sc1
	s_mov_b32 s0, 0x12000
	s_nop 0
	v_cvt_pk_bf16_f32 v132, v70, v71
	v_cvt_pk_bf16_f32 v133, v72, v73
	v_cvt_pk_bf16_f32 v134, v66, v67
	v_cvt_pk_bf16_f32 v135, v68, v69
	global_store_dwordx4 v[136:137], v[132:135], off offset:256 sc0 sc1
	v_add_co_u32_e32 v136, vcc, s59, v130
	s_nop 0
	v_cvt_pk_bf16_f32 v132, v62, v63
	v_cvt_pk_bf16_f32 v133, v64, v65
	v_cvt_pk_bf16_f32 v134, v58, v59
	v_cvt_pk_bf16_f32 v135, v60, v61
	s_nop 0
	v_addc_co_u32_e32 v137, vcc, 0, v131, vcc
	global_store_dwordx4 v[136:137], v[132:135], off sc0 sc1
	s_nop 1
	v_cvt_pk_bf16_f32 v132, v54, v55
	v_cvt_pk_bf16_f32 v133, v56, v57
	v_cvt_pk_bf16_f32 v134, v50, v51
	v_cvt_pk_bf16_f32 v135, v52, v53
	global_store_dwordx4 v[136:137], v[132:135], off offset:256 sc0 sc1
	v_add_co_u32_e32 v136, vcc, s0, v130
	s_nop 0
	v_cvt_pk_bf16_f32 v132, v46, v47
	v_cvt_pk_bf16_f32 v133, v48, v49
	v_cvt_pk_bf16_f32 v134, v42, v43
	v_cvt_pk_bf16_f32 v135, v44, v45
	s_nop 0
	v_addc_co_u32_e32 v137, vcc, 0, v131, vcc
	s_mov_b32 s0, 0x14000
	global_store_dwordx4 v[136:137], v[132:135], off sc0 sc1
	s_nop 1
	v_cvt_pk_bf16_f32 v132, v38, v39
	v_cvt_pk_bf16_f32 v133, v40, v41
	v_cvt_pk_bf16_f32 v134, v34, v35
	v_cvt_pk_bf16_f32 v135, v36, v37
	global_store_dwordx4 v[136:137], v[132:135], off offset:256 sc0 sc1
	v_add_co_u32_e32 v136, vcc, s0, v130
	s_nop 0
	v_cvt_pk_bf16_f32 v132, v30, v31
	v_cvt_pk_bf16_f32 v133, v32, v33
	v_cvt_pk_bf16_f32 v134, v26, v27
	v_cvt_pk_bf16_f32 v135, v28, v29
	s_nop 0
	v_addc_co_u32_e32 v137, vcc, 0, v131, vcc
	s_mov_b32 s0, 0x16000
	global_store_dwordx4 v[136:137], v[132:135], off sc0 sc1
	s_nop 1
	v_cvt_pk_bf16_f32 v132, v22, v23
	v_cvt_pk_bf16_f32 v133, v24, v25
	v_cvt_pk_bf16_f32 v134, v18, v19
	v_cvt_pk_bf16_f32 v135, v20, v21
	global_store_dwordx4 v[136:137], v[132:135], off offset:256 sc0 sc1
	v_add_co_u32_e32 v136, vcc, s0, v130
	s_nop 0
	v_cvt_pk_bf16_f32 v132, v14, v15
	v_cvt_pk_bf16_f32 v133, v16, v17
	s_nop 0
	v_addc_co_u32_e32 v137, vcc, 0, v131, vcc
	v_cvt_pk_bf16_f32 v134, v10, v11
	v_cvt_pk_bf16_f32 v135, v12, v13
	global_store_dwordx4 v[136:137], v[132:135], off sc0 sc1
	v_cvt_pk_bf16_f32 v130, v6, v7
	v_cvt_pk_bf16_f32 v131, v8, v9
	s_nop 1
	v_cvt_pk_bf16_f32 v132, v2, v3
	v_cvt_pk_bf16_f32 v133, v4, v5
	global_store_dwordx4 v[136:137], v[130:133], off offset:256 sc0 sc1
	s_cbranch_execnz .LBB9_1662
